# previous + first K-iteration of every GEMM tile peeled with C=0 on the first MFMA of each accumulator chain, removing the 128 per-tile accumulator zero-init v_movs
# speedup vs baseline: 1.0114x; 1.0114x over previous
; #define PG8_LAS __attribute__((address_space(3)))
; #define PG8_STAGE(bufoff, gbase, voff) do { _Pragma("unroll") for (int _i = 0; _i < 2; ++_i) \
;         __builtin_amdgcn_global_load_lds((const unsigned*)((const char*)(gbase) + (voff)[_i]), (PG8_LAS unsigned*)(lds + (bufoff) + ldsw + _i * (8 * USTR)), 16, 0, 0); } while (0)
; #define PG8_WAIT_V(n) asm volatile("s_waitcnt vmcnt(" #n ")" ::: "memory")
; #define PG8_WAIT_L(n) asm volatile("s_waitcnt lgkmcnt(" #n ")" ::: "memory")
; #define PG8_BAR __builtin_amdgcn_s_barrier()
; template <class Epi, class Sched, bool ALIGN_EPI, bool SP2>
; __device__ __forceinline__ void gemm_phase(PG8_LAS unsigned char* lds, const Gemm g, const Sched& S, const Epi& E, int wid) {
;     ...
;         const bool has_next = S.next(ui + 1, nxt);
;         const char* nA = has_next ? (const char*)g.A + (size_t)nxt.pm * tstepA : cA; const char* nB = has_next ? (const char*)g.Bt + (size_t)nxt.pn * tstepB : cB;
;         for (int t = 0; t < nt; t += 2) {
;             const bool last = (t == nt - 2);
;             const char* a1 = cA + (size_t)(t + 1) * kstep;
;             const char* a2 = last ? nA : cA + (size_t)(t + 2) * kstep; const char* b2 = last ? nB : cB + (size_t)(t + 2) * kstep;
;             const char* a3 = a2 + kstep; const char* b3 = b2 + kstep;
;             if constexpr (Epi::PRE == 1) { if (last) {
;                 const char* rsrc; const char* ssrc; E.pre(cur, rsrc, ssrc);
; #pragma unroll
;                 for (int _i = 0; _i < 2; ++_i) __builtin_amdgcn_global_load_lds((const unsigned*)(rsrc + (wid + 8 * _i) * 1024 + lane * 16), (PG8_LAS unsigned*)(lds + LDS_XOFF + (wid + 8 * _i) * 1024), 16, 0, 0);
;                 if (wid == 0) __builtin_amdgcn_global_load_lds((const unsigned*)(ssrc + lane * 16), (PG8_LAS unsigned*)(lds + LDS_XOFF + 16384), 16, 0, 0);
;             } }
;             if constexpr (SP2) {
;             PG8_LDB(B0, 0, 0); PG8_LDB(B1, 0, 1); PG8_SCHED; PG8_LDA(At, 0, 0); PG8_STAGE(PG8_SA(1, 1), a1 + hstepA, voffA);
;             PG8_WAIT_V(8); PG8_WAIT_L(0); PG8_BAR; PG8_MMA(0, 0, At, B0); PG8_MMA(0, 1, At, B1); PG8_BAR; PG8_SCHED;
;             PG8_LDA(At, 0, 1); PG8_STAGE(PG8_SB(0, 0), b2, voffB); PG8_STAGE(PG8_SB(0, 1), b2 + hstepB, voffB); PG8_STAGE(PG8_SA(0, 0), a2, voffA);
;             PG8_WAIT_V(8); PG8_WAIT_L(0); PG8_BAR; PG8_MMA(1, 0, At, B0); PG8_MMA(1, 1, At, B1); PG8_BAR; PG8_SCHED;
.LBB0_149:
	s_ashr_i32 s69, s68, 31
	s_lshl_b64 s[26:27], s[68:69], 20
	s_add_u32 s70, s30, s26
	s_addc_u32 s71, s31, s27
	s_and_b64 s[26:27], s[36:37], exec
	s_cselect_b32 s26, s71, s39
	s_cselect_b32 s27, s70, s38
	s_ashr_i32 s23, s22, 31
	s_lshl_b64 s[72:73], s[22:23], 19
	v_readlane_b32 s23, v255, 12
	s_add_u32 s72, s23, s72
	v_readlane_b32 s23, v255, 13
	s_addc_u32 s73, s23, s73
	s_and_b64 s[74:75], s[36:37], exec
	s_cselect_b32 s23, s73, s41
	s_cselect_b32 s69, s72, s40
	s_add_u32 s38, s38, 0x80080
	s_addc_u32 s39, s39, 0
	s_add_u32 s78, s40, 0x100
	s_addc_u32 s79, s41, 0
	s_mov_b32 s89, -2
	s_waitcnt vmcnt(0)
	s_add_u32 s40, s38, 0xfff80080
	s_addc_u32 s41, s39, -1
	s_add_i32 s95, 0, 0x11000
	s_cmp_eq_u32 s89, 12
	s_cselect_b32 s75, s26, s41
	s_cselect_b32 s74, s27, s40
	s_cselect_b32 s41, s23, s79
	s_cselect_b32 s40, s69, s78
	s_add_i32 s44, 0, 0x15400
	v_add_u32_e32 v60, s95, v216
	v_add_u32_e32 v156, s44, v216
	ds_read_b128 v[48:51], v60
	ds_read_b128 v[52:55], v60 offset:64
	ds_read_b128 v[56:59], v60 offset:2176
	ds_read_b128 v[60:63], v60 offset:2240
	ds_read_b128 v[144:147], v156
	ds_read_b128 v[148:151], v156 offset:64
	ds_read_b128 v[152:155], v156 offset:2176
	ds_read_b128 v[156:159], v156 offset:2240
	v_lshl_add_u64 v[198:199], s[38:39], 0, v[168:169]
	s_add_i32 m0, s0, 0xcc00
	ds_read_b128 v[172:175], v217
	ds_read_b128 v[176:179], v217 offset:64
	ds_read_b128 v[180:183], v217 offset:2176
	ds_read_b128 v[184:187], v217 offset:2240
	ds_read_b128 v[188:191], v217 offset:4352
	ds_read_b128 v[208:211], v217 offset:4416
	ds_read_b128 v[212:215], v217 offset:6528
	ds_read_b128 v[218:221], v217 offset:6592
	global_load_lds_dwordx4 v[198:199], off
	v_lshl_add_u64 v[198:199], s[38:39], 0, v[170:171]
	s_add_i32 m0, s0, 0xee00
	s_nop 0
	global_load_lds_dwordx4 v[198:199], off
	s_waitcnt vmcnt(8)
	s_waitcnt lgkmcnt(0)
	s_barrier
	s_setprio 1
	s_waitcnt lgkmcnt(0)
	v_mfma_f32_16x16x32_bf16 v[140:143], v[48:51], v[172:175], 0
	v_mfma_f32_16x16x32_bf16 v[136:139], v[56:59], v[172:175], 0
	v_mfma_f32_16x16x32_bf16 v[124:127], v[48:51], v[180:183], 0
	v_mfma_f32_16x16x32_bf16 v[120:123], v[56:59], v[180:183], 0
	v_mfma_f32_16x16x32_bf16 v[108:111], v[48:51], v[188:191], 0
	v_mfma_f32_16x16x32_bf16 v[104:107], v[56:59], v[188:191], 0
	v_mfma_f32_16x16x32_bf16 v[92:95], v[48:51], v[212:215], 0
	v_mfma_f32_16x16x32_bf16 v[88:91], v[56:59], v[212:215], 0
	v_mfma_f32_16x16x32_bf16 v[140:143], v[52:55], v[176:179], v[140:143]
	v_mfma_f32_16x16x32_bf16 v[136:139], v[60:63], v[176:179], v[136:139]
	v_mfma_f32_16x16x32_bf16 v[124:127], v[52:55], v[184:187], v[124:127]
	v_mfma_f32_16x16x32_bf16 v[120:123], v[60:63], v[184:187], v[120:123]
	v_mfma_f32_16x16x32_bf16 v[108:111], v[52:55], v[208:211], v[108:111]
	v_mfma_f32_16x16x32_bf16 v[104:107], v[60:63], v[208:211], v[104:107]
	v_mfma_f32_16x16x32_bf16 v[92:95], v[52:55], v[218:221], v[92:95]
	v_mfma_f32_16x16x32_bf16 v[88:91], v[60:63], v[218:221], v[88:91]
	s_setprio 0
	s_setprio 1
	v_mfma_f32_16x16x32_bf16 v[132:135], v[144:147], v[172:175], 0
	v_mfma_f32_16x16x32_bf16 v[128:131], v[152:155], v[172:175], 0
	v_mfma_f32_16x16x32_bf16 v[116:119], v[144:147], v[180:183], 0
	v_mfma_f32_16x16x32_bf16 v[112:115], v[152:155], v[180:183], 0
	v_mfma_f32_16x16x32_bf16 v[100:103], v[144:147], v[188:191], 0
	v_mfma_f32_16x16x32_bf16 v[96:99], v[152:155], v[188:191], 0
	v_mfma_f32_16x16x32_bf16 v[84:87], v[144:147], v[212:215], 0
	v_mfma_f32_16x16x32_bf16 v[80:83], v[152:155], v[212:215], 0
	v_mfma_f32_16x16x32_bf16 v[132:135], v[148:151], v[176:179], v[132:135]
	v_mfma_f32_16x16x32_bf16 v[128:131], v[156:159], v[176:179], v[128:131]
	v_mfma_f32_16x16x32_bf16 v[116:119], v[148:151], v[184:187], v[116:119]
	v_mfma_f32_16x16x32_bf16 v[112:115], v[156:159], v[184:187], v[112:115]
	v_mfma_f32_16x16x32_bf16 v[100:103], v[148:151], v[208:211], v[100:103]
	v_mfma_f32_16x16x32_bf16 v[96:99], v[156:159], v[208:211], v[96:99]
	v_mfma_f32_16x16x32_bf16 v[84:87], v[148:151], v[218:221], v[84:87]
	v_mfma_f32_16x16x32_bf16 v[80:83], v[156:159], v[218:221], v[80:83]
	s_setprio 0
	s_barrier
	s_add_i32 s45, s95, s33
	v_lshl_add_u64 v[198:199], s[40:41], 0, v[192:193]
	s_mov_b32 m0, s45
	ds_read_b128 v[172:175], v217 offset:17408
	ds_read_b128 v[176:179], v217 offset:17472
	ds_read_b128 v[180:183], v217 offset:19584
	ds_read_b128 v[184:187], v217 offset:19648
	ds_read_b128 v[188:191], v217 offset:21760
	ds_read_b128 v[208:211], v217 offset:21824
	ds_read_b128 v[212:215], v217 offset:23936
	ds_read_b128 v[218:221], v217 offset:24000
	global_load_lds_dwordx4 v[198:199], off
	s_add_i32 m0, s45, 0x2200
	s_add_u32 vcc_lo, s40, 0x40000
	v_lshl_add_u64 v[200:201], s[40:41], 0, v[160:161]
	s_addc_u32 vcc_hi, s41, 0
	s_add_i32 s44, s44, s33
	global_load_lds_dwordx4 v[200:201], off
	v_lshl_add_u64 v[222:223], vcc, 0, v[192:193]
	s_mov_b32 m0, s44
	v_lshl_add_u64 v[224:225], s[74:75], 0, v[162:163]
	global_load_lds_dwordx4 v[222:223], off
	v_lshl_add_u64 v[222:223], vcc, 0, v[160:161]
	s_add_i32 m0, s44, 0x2200
	s_nop 0
	global_load_lds_dwordx4 v[222:223], off
	v_lshl_add_u64 v[222:223], s[74:75], 0, v[164:165]
	s_mov_b32 m0, s0
	s_nop 0
	global_load_lds_dwordx4 v[222:223], off
	s_mov_b32 m0, s5
	s_nop 0
	global_load_lds_dwordx4 v[224:225], off
	s_waitcnt vmcnt(8)
	s_waitcnt lgkmcnt(0)
	s_barrier
; #define PG8_STAGE(bufoff, gbase, voff) do { _Pragma("unroll") for (int _i = 0; _i < 2; ++_i) \
;         __builtin_amdgcn_global_load_lds((const unsigned*)((const char*)(gbase) + (voff)[_i]), (PG8_LAS unsigned*)(lds + (bufoff) + ldsw + _i * (8 * USTR)), 16, 0, 0); } while (0)
; #define PG8_LDA(dst, b, h) do { _Pragma("unroll") for (int m = 0; m < 4; ++m) _Pragma("unroll") for (int k = 0; k < 2; ++k) dst[m][k] = *(const PG8_LAS bf16x8*)(lds + PG8_SA(b, h) + aoff + m * (2 * USTR) + k * 64); } while (0)
; #define PG8_LDB(dst, b, h) do { _Pragma("unroll") for (int n = 0; n < 2; ++n) _Pragma("unroll") for (int k = 0; k < 2; ++k) dst[n][k] = *(const PG8_LAS bf16x8*)(lds + PG8_SB(b, h) + boff + n * (2 * USTR) + k * 64); } while (0)
; #define PG8_MMA(ai, bj, At, Bt) do { __builtin_amdgcn_s_setprio(1); _Pragma("unroll") for (int m = 0; m < 4; ++m) _Pragma("unroll") for (int n = 0; n < 2; ++n) _Pragma("unroll") for (int k = 0; k < 2; ++k) \
;         acc[ai][bj][m][n] = __builtin_amdgcn_mfma_f32_16x16x32_bf16(Bt[n][k], At[m][k], acc[ai][bj][m][n], 0, 0, 0); __builtin_amdgcn_s_setprio(0); } while (0)
; #define PG8_WAIT_V(n) asm volatile("s_waitcnt vmcnt(" #n ")" ::: "memory")
; #define PG8_WAIT_L(n) asm volatile("s_waitcnt lgkmcnt(" #n ")" ::: "memory")
; #define PG8_BAR __builtin_amdgcn_s_barrier()
; #define PG8_SCHED __builtin_amdgcn_sched_barrier(0)
; template <class Epi, class Sched, bool ALIGN_EPI, bool SP2>
; __device__ __forceinline__ void gemm_phase(PG8_LAS unsigned char* lds, const Gemm g, const Sched& S, const Epi& E, int wid) {
;     ...
;             PG8_WAIT_V(8); PG8_WAIT_L(0); PG8_BAR; PG8_MMA(1, 0, At, B0); PG8_MMA(1, 1, At, B1); PG8_BAR; PG8_SCHED;
;             PG8_LDB(B0, 1, 0); PG8_LDB(B1, 1, 1); PG8_SCHED; PG8_LDA(At, 1, 0); PG8_STAGE(PG8_SA(0, 1), a2 + hstepA, voffA);
;             PG8_WAIT_V(8); PG8_WAIT_L(0); PG8_BAR; PG8_MMA(0, 0, At, B0); PG8_MMA(0, 1, At, B1); PG8_BAR; PG8_SCHED;
	s_setprio 1
	s_waitcnt lgkmcnt(0)
	v_mfma_f32_16x16x32_bf16 v[76:79], v[48:51], v[172:175], 0
	v_mfma_f32_16x16x32_bf16 v[72:75], v[56:59], v[172:175], 0
	v_mfma_f32_16x16x32_bf16 v[44:47], v[48:51], v[180:183], 0
	v_mfma_f32_16x16x32_bf16 v[40:43], v[56:59], v[180:183], 0
	v_mfma_f32_16x16x32_bf16 v[24:27], v[48:51], v[188:191], 0
	v_mfma_f32_16x16x32_bf16 v[28:31], v[56:59], v[188:191], 0
	v_mfma_f32_16x16x32_bf16 v[4:7], v[48:51], v[212:215], 0
	v_mfma_f32_16x16x32_bf16 v[12:15], v[56:59], v[212:215], 0
	v_mfma_f32_16x16x32_bf16 v[76:79], v[52:55], v[176:179], v[76:79]
	v_mfma_f32_16x16x32_bf16 v[72:75], v[60:63], v[176:179], v[72:75]
	v_mfma_f32_16x16x32_bf16 v[44:47], v[52:55], v[184:187], v[44:47]
	v_mfma_f32_16x16x32_bf16 v[40:43], v[60:63], v[184:187], v[40:43]
	v_mfma_f32_16x16x32_bf16 v[24:27], v[52:55], v[208:211], v[24:27]
	v_mfma_f32_16x16x32_bf16 v[28:31], v[60:63], v[208:211], v[28:31]
	v_mfma_f32_16x16x32_bf16 v[4:7], v[52:55], v[218:221], v[4:7]
	v_mfma_f32_16x16x32_bf16 v[12:15], v[60:63], v[218:221], v[12:15]
	s_setprio 0
	s_setprio 1
	v_mfma_f32_16x16x32_bf16 v[36:39], v[144:147], v[180:183], 0
	v_mfma_f32_16x16x32_bf16 v[32:35], v[152:155], v[180:183], 0
	v_mfma_f32_16x16x32_bf16 v[20:23], v[144:147], v[188:191], 0
	v_mfma_f32_16x16x32_bf16 v[16:19], v[152:155], v[188:191], 0
	v_mfma_f32_16x16x32_bf16 v[8:11], v[144:147], v[212:215], 0
	v_mfma_f32_16x16x32_bf16 v[0:3], v[152:155], v[212:215], 0
	v_mfma_f32_16x16x32_bf16 v[48:51], v[144:147], v[172:175], 0
	v_mfma_f32_16x16x32_bf16 v[52:55], v[152:155], v[172:175], 0
	v_mfma_f32_16x16x32_bf16 v[36:39], v[148:151], v[184:187], v[36:39]
	v_mfma_f32_16x16x32_bf16 v[32:35], v[156:159], v[184:187], v[32:35]
	v_mfma_f32_16x16x32_bf16 v[20:23], v[148:151], v[208:211], v[20:23]
	v_mfma_f32_16x16x32_bf16 v[16:19], v[156:159], v[208:211], v[16:19]
	v_mfma_f32_16x16x32_bf16 v[8:11], v[148:151], v[218:221], v[8:11]
	v_mfma_f32_16x16x32_bf16 v[0:3], v[156:159], v[218:221], v[0:3]
	v_mfma_f32_16x16x32_bf16 v[48:51], v[148:151], v[176:179], v[48:51]
	v_mfma_f32_16x16x32_bf16 v[52:55], v[156:159], v[176:179], v[52:55]
	s_setprio 0
	s_barrier
	s_add_i32 s44, 0, 0x19800
	s_add_i32 s45, 0, 0x1dc00
	v_add_u32_e32 v68, s44, v216
	v_add_u32_e32 v156, s45, v216
	ds_read_b128 v[56:59], v68
	ds_read_b128 v[60:63], v68 offset:64
	ds_read_b128 v[64:67], v68 offset:2176
	ds_read_b128 v[68:71], v68 offset:2240
	ds_read_b128 v[144:147], v156
	ds_read_b128 v[148:151], v156 offset:64
	ds_read_b128 v[152:155], v156 offset:2176
	ds_read_b128 v[156:159], v156 offset:2240
	s_add_u32 s74, s74, 0x80000
	s_addc_u32 s75, s75, 0
	s_mov_b32 m0, s29
	v_lshl_add_u64 v[226:227], s[74:75], 0, v[164:165]
	ds_read_b128 v[172:175], v217 offset:34816
	ds_read_b128 v[176:179], v217 offset:34880
	ds_read_b128 v[180:183], v217 offset:36992
	ds_read_b128 v[184:187], v217 offset:37056
	ds_read_b128 v[188:191], v217 offset:39168
	ds_read_b128 v[208:211], v217 offset:39232
	ds_read_b128 v[212:215], v217 offset:41344
	ds_read_b128 v[218:221], v217 offset:41408
	global_load_lds_dwordx4 v[226:227], off
	v_lshl_add_u64 v[226:227], s[74:75], 0, v[162:163]
	s_mov_b32 m0, s56
	s_nop 0
	global_load_lds_dwordx4 v[226:227], off
	s_waitcnt vmcnt(8)
	s_waitcnt lgkmcnt(0)
	s_barrier
	s_setprio 1
	s_waitcnt lgkmcnt(0)
	v_mfma_f32_16x16x32_bf16 v[140:143], v[56:59], v[172:175], v[140:143]
	v_mfma_f32_16x16x32_bf16 v[136:139], v[64:67], v[172:175], v[136:139]
	v_mfma_f32_16x16x32_bf16 v[124:127], v[56:59], v[180:183], v[124:127]
	v_mfma_f32_16x16x32_bf16 v[120:123], v[64:67], v[180:183], v[120:123]
	v_mfma_f32_16x16x32_bf16 v[108:111], v[56:59], v[188:191], v[108:111]
	v_mfma_f32_16x16x32_bf16 v[104:107], v[64:67], v[188:191], v[104:107]
	v_mfma_f32_16x16x32_bf16 v[92:95], v[56:59], v[212:215], v[92:95]
	v_mfma_f32_16x16x32_bf16 v[88:91], v[64:67], v[212:215], v[88:91]
	v_mfma_f32_16x16x32_bf16 v[140:143], v[60:63], v[176:179], v[140:143]
	v_mfma_f32_16x16x32_bf16 v[136:139], v[68:71], v[176:179], v[136:139]
	v_mfma_f32_16x16x32_bf16 v[124:127], v[60:63], v[184:187], v[124:127]
	v_mfma_f32_16x16x32_bf16 v[120:123], v[68:71], v[184:187], v[120:123]
	v_mfma_f32_16x16x32_bf16 v[108:111], v[60:63], v[208:211], v[108:111]
	v_mfma_f32_16x16x32_bf16 v[104:107], v[68:71], v[208:211], v[104:107]
	v_mfma_f32_16x16x32_bf16 v[92:95], v[60:63], v[218:221], v[92:95]
	v_mfma_f32_16x16x32_bf16 v[88:91], v[68:71], v[218:221], v[88:91]
	s_setprio 0
	s_setprio 1
	v_mfma_f32_16x16x32_bf16 v[132:135], v[144:147], v[172:175], v[132:135]
	v_mfma_f32_16x16x32_bf16 v[128:131], v[152:155], v[172:175], v[128:131]
	v_mfma_f32_16x16x32_bf16 v[116:119], v[144:147], v[180:183], v[116:119]
	v_mfma_f32_16x16x32_bf16 v[112:115], v[152:155], v[180:183], v[112:115]
	v_mfma_f32_16x16x32_bf16 v[100:103], v[144:147], v[188:191], v[100:103]
	v_mfma_f32_16x16x32_bf16 v[96:99], v[152:155], v[188:191], v[96:99]
	v_mfma_f32_16x16x32_bf16 v[84:87], v[144:147], v[212:215], v[84:87]
	v_mfma_f32_16x16x32_bf16 v[80:83], v[152:155], v[212:215], v[80:83]
	v_mfma_f32_16x16x32_bf16 v[132:135], v[148:151], v[176:179], v[132:135]
	v_mfma_f32_16x16x32_bf16 v[128:131], v[156:159], v[176:179], v[128:131]
	v_mfma_f32_16x16x32_bf16 v[116:119], v[148:151], v[184:187], v[116:119]
	v_mfma_f32_16x16x32_bf16 v[112:115], v[156:159], v[184:187], v[112:115]
	v_mfma_f32_16x16x32_bf16 v[100:103], v[148:151], v[208:211], v[100:103]
	v_mfma_f32_16x16x32_bf16 v[96:99], v[156:159], v[208:211], v[96:99]
	v_mfma_f32_16x16x32_bf16 v[84:87], v[148:151], v[218:221], v[84:87]
	v_mfma_f32_16x16x32_bf16 v[80:83], v[156:159], v[218:221], v[80:83]
	s_setprio 0
	s_barrier
; #define PG8_STAGE(bufoff, gbase, voff) do { _Pragma("unroll") for (int _i = 0; _i < 2; ++_i) \
;         __builtin_amdgcn_global_load_lds((const unsigned*)((const char*)(gbase) + (voff)[_i]), (PG8_LAS unsigned*)(lds + (bufoff) + ldsw + _i * (8 * USTR)), 16, 0, 0); } while (0)
; #define PG8_LDA(dst, b, h) do { _Pragma("unroll") for (int m = 0; m < 4; ++m) _Pragma("unroll") for (int k = 0; k < 2; ++k) dst[m][k] = *(const PG8_LAS bf16x8*)(lds + PG8_SA(b, h) + aoff + m * (2 * USTR) + k * 64); } while (0)
; #define PG8_MMA(ai, bj, At, Bt) do { __builtin_amdgcn_s_setprio(1); _Pragma("unroll") for (int m = 0; m < 4; ++m) _Pragma("unroll") for (int n = 0; n < 2; ++n) _Pragma("unroll") for (int k = 0; k < 2; ++k) \
;         acc[ai][bj][m][n] = __builtin_amdgcn_mfma_f32_16x16x32_bf16(Bt[n][k], At[m][k], acc[ai][bj][m][n], 0, 0, 0); __builtin_amdgcn_s_setprio(0); } while (0)
; #define PG8_WAIT_V(n) asm volatile("s_waitcnt vmcnt(" #n ")" ::: "memory")
; #define PG8_WAIT_L(n) asm volatile("s_waitcnt lgkmcnt(" #n ")" ::: "memory")
; #define PG8_BAR __builtin_amdgcn_s_barrier()
; #define PG8_SCHED __builtin_amdgcn_sched_barrier(0)
; template <class Epi, class Sched, bool ALIGN_EPI, bool SP2>
; __device__ __forceinline__ void gemm_phase(PG8_LAS unsigned char* lds, const Gemm g, const Sched& S, const Epi& E, int wid) {
;     ...
;             PG8_LDA(At, 1, 1); PG8_STAGE(PG8_SB(1, 0), b3, voffB); PG8_STAGE(PG8_SB(1, 1), b3 + hstepB, voffB); PG8_STAGE(PG8_SA(1, 0), a3, voffA);
;             PG8_WAIT_V(8); PG8_WAIT_L(0); PG8_BAR; PG8_MMA(1, 0, At, B0); PG8_MMA(1, 1, At, B1); PG8_BAR; PG8_SCHED;
	s_add_i32 s44, s44, s33
	v_lshl_add_u64 v[198:199], v[198:199], 0, s[6:7]
	s_mov_b32 m0, s44
	ds_read_b128 v[172:175], v217 offset:52224
	ds_read_b128 v[176:179], v217 offset:52288
	ds_read_b128 v[180:183], v217 offset:54400
	ds_read_b128 v[184:187], v217 offset:54464
	ds_read_b128 v[188:191], v217 offset:56576
	ds_read_b128 v[208:211], v217 offset:56640
	ds_read_b128 v[212:215], v217 offset:58752
	ds_read_b128 v[218:221], v217 offset:58816
	global_load_lds_dwordx4 v[198:199], off
	s_add_i32 m0, s44, 0x2200
	s_add_u32 s40, s40, 0x40080
	v_lshl_add_u64 v[198:199], v[200:201], 0, s[6:7]
	s_addc_u32 s41, s41, 0
	s_add_i32 s44, s45, s33
	global_load_lds_dwordx4 v[198:199], off
	v_lshl_add_u64 v[198:199], s[40:41], 0, v[192:193]
	s_mov_b32 m0, s44
	s_nop 0
	global_load_lds_dwordx4 v[198:199], off
	v_lshl_add_u64 v[198:199], s[40:41], 0, v[160:161]
	s_add_i32 m0, s44, 0x2200
	s_nop 0
	global_load_lds_dwordx4 v[198:199], off
	v_lshl_add_u64 v[198:199], v[222:223], 0, s[6:7]
	s_mov_b32 m0, s57
	s_nop 0
	global_load_lds_dwordx4 v[198:199], off
	v_lshl_add_u64 v[198:199], v[224:225], 0, s[6:7]
	s_mov_b32 m0, s76
	s_nop 0
	global_load_lds_dwordx4 v[198:199], off
	s_waitcnt vmcnt(8)
	s_waitcnt lgkmcnt(0)
	s_barrier
	s_setprio 1
	s_waitcnt lgkmcnt(0)
	v_mfma_f32_16x16x32_bf16 v[76:79], v[56:59], v[172:175], v[76:79]
	v_mfma_f32_16x16x32_bf16 v[72:75], v[64:67], v[172:175], v[72:75]
	v_mfma_f32_16x16x32_bf16 v[44:47], v[56:59], v[180:183], v[44:47]
	v_mfma_f32_16x16x32_bf16 v[40:43], v[64:67], v[180:183], v[40:43]
	v_mfma_f32_16x16x32_bf16 v[24:27], v[56:59], v[188:191], v[24:27]
	v_mfma_f32_16x16x32_bf16 v[28:31], v[64:67], v[188:191], v[28:31]
	v_mfma_f32_16x16x32_bf16 v[4:7], v[56:59], v[212:215], v[4:7]
	v_mfma_f32_16x16x32_bf16 v[12:15], v[64:67], v[212:215], v[12:15]
	v_mfma_f32_16x16x32_bf16 v[76:79], v[60:63], v[176:179], v[76:79]
	v_mfma_f32_16x16x32_bf16 v[72:75], v[68:71], v[176:179], v[72:75]
	v_mfma_f32_16x16x32_bf16 v[44:47], v[60:63], v[184:187], v[44:47]
	v_mfma_f32_16x16x32_bf16 v[40:43], v[68:71], v[184:187], v[40:43]
	v_mfma_f32_16x16x32_bf16 v[24:27], v[60:63], v[208:211], v[24:27]
	v_mfma_f32_16x16x32_bf16 v[28:31], v[68:71], v[208:211], v[28:31]
	v_mfma_f32_16x16x32_bf16 v[4:7], v[60:63], v[218:221], v[4:7]
	v_mfma_f32_16x16x32_bf16 v[12:15], v[68:71], v[218:221], v[12:15]
	s_setprio 0
	s_setprio 1
	v_mfma_f32_16x16x32_bf16 v[48:51], v[144:147], v[172:175], v[48:51]
	v_mfma_f32_16x16x32_bf16 v[68:71], v[148:151], v[176:179], v[48:51]
	v_mfma_f32_16x16x32_bf16 v[48:51], v[152:155], v[172:175], v[52:55]
	v_mfma_f32_16x16x32_bf16 v[36:39], v[144:147], v[180:183], v[36:39]
	v_mfma_f32_16x16x32_bf16 v[32:35], v[152:155], v[180:183], v[32:35]
	v_mfma_f32_16x16x32_bf16 v[20:23], v[144:147], v[188:191], v[20:23]
	v_mfma_f32_16x16x32_bf16 v[16:19], v[152:155], v[188:191], v[16:19]
	v_mfma_f32_16x16x32_bf16 v[8:11], v[144:147], v[212:215], v[8:11]
	v_mfma_f32_16x16x32_bf16 v[0:3], v[152:155], v[212:215], v[0:3]
	v_mfma_f32_16x16x32_bf16 v[64:67], v[156:159], v[176:179], v[48:51]
	v_mfma_f32_16x16x32_bf16 v[36:39], v[148:151], v[184:187], v[36:39]
	v_mfma_f32_16x16x32_bf16 v[32:35], v[156:159], v[184:187], v[32:35]
	v_mfma_f32_16x16x32_bf16 v[20:23], v[148:151], v[208:211], v[20:23]
	v_mfma_f32_16x16x32_bf16 v[16:19], v[156:159], v[208:211], v[16:19]
	v_mfma_f32_16x16x32_bf16 v[8:11], v[148:151], v[218:221], v[8:11]
	v_mfma_f32_16x16x32_bf16 v[0:3], v[156:159], v[218:221], v[0:3]
	s_setprio 0
	s_barrier
	s_add_i32 s89, s89, 2
	s_add_u32 s38, s38, 0x100
	s_addc_u32 s39, s39, 0
	s_add_u32 s78, s78, 0x100
	s_addc_u32 s79, s79, 0
	s_cmp_gt_u32 s89, 13

; #define PG8_LAS __attribute__((address_space(3)))
; #define PG8_STAGE(bufoff, gbase, voff) do { _Pragma("unroll") for (int _i = 0; _i < 2; ++_i) \
;         __builtin_amdgcn_global_load_lds((const unsigned*)((const char*)(gbase) + (voff)[_i]), (PG8_LAS unsigned*)(lds + (bufoff) + ldsw + _i * (8 * USTR)), 16, 0, 0); } while (0)
; #define PG8_WAIT_V(n) asm volatile("s_waitcnt vmcnt(" #n ")" ::: "memory")
; #define PG8_WAIT_L(n) asm volatile("s_waitcnt lgkmcnt(" #n ")" ::: "memory")
; #define PG8_BAR __builtin_amdgcn_s_barrier()
; template <class Epi, class Sched, bool ALIGN_EPI, bool SP2>
; __device__ __forceinline__ void gemm_phase(PG8_LAS unsigned char* lds, const Gemm g, const Sched& S, const Epi& E, int wid) {
;     ...
;         const bool has_next = S.next(ui + 1, nxt);
;         const char* nA = has_next ? (const char*)g.A + (size_t)nxt.pm * tstepA : cA; const char* nB = has_next ? (const char*)g.Bt + (size_t)nxt.pn * tstepB : cB;
;         for (int t = 0; t < nt; t += 2) {
;             const bool last = (t == nt - 2);
;             const char* a1 = cA + (size_t)(t + 1) * kstep;
;             const char* a2 = last ? nA : cA + (size_t)(t + 2) * kstep; const char* b2 = last ? nB : cB + (size_t)(t + 2) * kstep;
;             const char* a3 = a2 + kstep; const char* b3 = b2 + kstep;
;             if constexpr (Epi::PRE == 1) { if (last) {
;                 const char* rsrc; const char* ssrc; E.pre(cur, rsrc, ssrc);
; #pragma unroll
;                 for (int _i = 0; _i < 2; ++_i) __builtin_amdgcn_global_load_lds((const unsigned*)(rsrc + (wid + 8 * _i) * 1024 + lane * 16), (PG8_LAS unsigned*)(lds + LDS_XOFF + (wid + 8 * _i) * 1024), 16, 0, 0);
;                 if (wid == 0) __builtin_amdgcn_global_load_lds((const unsigned*)(ssrc + lane * 16), (PG8_LAS unsigned*)(lds + LDS_XOFF + 16384), 16, 0, 0);
;             } }
;             if constexpr (SP2) {
;             PG8_LDB(B0, 0, 0); PG8_LDB(B1, 0, 1); PG8_SCHED; PG8_LDA(At, 0, 0); PG8_STAGE(PG8_SA(1, 1), a1 + hstepA, voffA);
;             PG8_WAIT_V(8); PG8_WAIT_L(0); PG8_BAR; PG8_MMA(0, 0, At, B0); PG8_MMA(0, 1, At, B1); PG8_BAR; PG8_SCHED;
;             PG8_LDA(At, 0, 1); PG8_STAGE(PG8_SB(0, 0), b2, voffB); PG8_STAGE(PG8_SB(0, 1), b2 + hstepB, voffB); PG8_STAGE(PG8_SA(0, 0), a2, voffA);
;             PG8_WAIT_V(8); PG8_WAIT_L(0); PG8_BAR; PG8_MMA(1, 0, At, B0); PG8_MMA(1, 1, At, B1); PG8_BAR; PG8_SCHED;
.LBB0_289:
	s_add_u32 s38, s42, 0xb0080
	s_addc_u32 s39, s43, 0
	s_add_u32 s26, s40, 0x100
	s_addc_u32 s27, s41, 0
	s_mov_b32 s68, -2
	s_waitcnt vmcnt(0)
	s_add_u32 s40, s38, 0xfff50080
	s_addc_u32 s41, s39, -1
	s_add_i32 s69, 0, 0x11000
	s_cmp_eq_u32 s68, 40
	s_cselect_b32 s43, s23, s41
	s_cselect_b32 s42, s22, s40
	s_cselect_b32 s41, s45, s27
	s_cselect_b32 s40, s44, s26
	s_add_i32 s76, 0, 0x15400
	v_add_u32_e32 v52, s69, v197
	v_add_u32_e32 v156, s76, v197
	ds_read_b128 v[40:43], v52
	ds_read_b128 v[44:47], v52 offset:64
	ds_read_b128 v[48:51], v52 offset:2176
	ds_read_b128 v[52:55], v52 offset:2240
	ds_read_b128 v[144:147], v156
	ds_read_b128 v[148:151], v156 offset:64
	ds_read_b128 v[152:155], v156 offset:2176
	ds_read_b128 v[156:159], v156 offset:2240
	v_lshl_add_u64 v[198:199], s[38:39], 0, v[212:213]
	s_add_i32 m0, s0, 0xcc00
	ds_read_b128 v[160:163], v241
	ds_read_b128 v[164:167], v241 offset:64
	ds_read_b128 v[168:171], v241 offset:2176
	ds_read_b128 v[172:175], v241 offset:2240
	ds_read_b128 v[176:179], v241 offset:4352
	ds_read_b128 v[180:183], v241 offset:4416
	ds_read_b128 v[184:187], v241 offset:6528
	ds_read_b128 v[188:191], v241 offset:6592
	global_load_lds_dwordx4 v[198:199], off
	v_lshl_add_u64 v[198:199], s[38:39], 0, v[214:215]
	s_add_i32 m0, s0, 0xee00
	s_nop 0
	global_load_lds_dwordx4 v[198:199], off
	s_waitcnt vmcnt(8)
	s_waitcnt lgkmcnt(0)
	s_barrier
	s_setprio 1
	s_waitcnt lgkmcnt(0)
	v_mfma_f32_16x16x32_bf16 v[132:135], v[40:43], v[160:163], 0
	v_mfma_f32_16x16x32_bf16 v[128:131], v[48:51], v[160:163], 0
	v_mfma_f32_16x16x32_bf16 v[124:127], v[40:43], v[168:171], 0
	v_mfma_f32_16x16x32_bf16 v[120:123], v[48:51], v[168:171], 0
	v_mfma_f32_16x16x32_bf16 v[108:111], v[40:43], v[176:179], 0
	v_mfma_f32_16x16x32_bf16 v[104:107], v[48:51], v[176:179], 0
	v_mfma_f32_16x16x32_bf16 v[92:95], v[40:43], v[184:187], 0
	v_mfma_f32_16x16x32_bf16 v[88:91], v[48:51], v[184:187], 0
	v_mfma_f32_16x16x32_bf16 v[132:135], v[44:47], v[164:167], v[132:135]
	v_mfma_f32_16x16x32_bf16 v[128:131], v[52:55], v[164:167], v[128:131]
	v_mfma_f32_16x16x32_bf16 v[124:127], v[44:47], v[172:175], v[124:127]
	v_mfma_f32_16x16x32_bf16 v[120:123], v[52:55], v[172:175], v[120:123]
	v_mfma_f32_16x16x32_bf16 v[108:111], v[44:47], v[180:183], v[108:111]
	v_mfma_f32_16x16x32_bf16 v[104:107], v[52:55], v[180:183], v[104:107]
	v_mfma_f32_16x16x32_bf16 v[92:95], v[44:47], v[188:191], v[92:95]
	v_mfma_f32_16x16x32_bf16 v[88:91], v[52:55], v[188:191], v[88:91]
	s_setprio 0
	s_setprio 1
	v_mfma_f32_16x16x32_bf16 v[140:143], v[144:147], v[160:163], 0
	v_mfma_f32_16x16x32_bf16 v[136:139], v[152:155], v[160:163], 0
	v_mfma_f32_16x16x32_bf16 v[116:119], v[144:147], v[168:171], 0
	v_mfma_f32_16x16x32_bf16 v[112:115], v[152:155], v[168:171], 0
	v_mfma_f32_16x16x32_bf16 v[100:103], v[144:147], v[176:179], 0
	v_mfma_f32_16x16x32_bf16 v[96:99], v[152:155], v[176:179], 0
	v_mfma_f32_16x16x32_bf16 v[84:87], v[144:147], v[184:187], 0
	v_mfma_f32_16x16x32_bf16 v[80:83], v[152:155], v[184:187], 0
	v_mfma_f32_16x16x32_bf16 v[140:143], v[148:151], v[164:167], v[140:143]
	v_mfma_f32_16x16x32_bf16 v[136:139], v[156:159], v[164:167], v[136:139]
	v_mfma_f32_16x16x32_bf16 v[116:119], v[148:151], v[172:175], v[116:119]
	v_mfma_f32_16x16x32_bf16 v[112:115], v[156:159], v[172:175], v[112:115]
	v_mfma_f32_16x16x32_bf16 v[100:103], v[148:151], v[180:183], v[100:103]
	v_mfma_f32_16x16x32_bf16 v[96:99], v[156:159], v[180:183], v[96:99]
	v_mfma_f32_16x16x32_bf16 v[84:87], v[148:151], v[188:191], v[84:87]
	v_mfma_f32_16x16x32_bf16 v[80:83], v[156:159], v[188:191], v[80:83]
	s_setprio 0
	s_barrier
	s_add_i32 s69, s69, s33
	v_lshl_add_u64 v[198:199], s[40:41], 0, v[208:209]
	s_mov_b32 m0, s69
	ds_read_b128 v[160:163], v241 offset:17408
	ds_read_b128 v[164:167], v241 offset:17472
	ds_read_b128 v[168:171], v241 offset:19584
	ds_read_b128 v[172:175], v241 offset:19648
	ds_read_b128 v[176:179], v241 offset:21760
	ds_read_b128 v[180:183], v241 offset:21824
	ds_read_b128 v[184:187], v241 offset:23936
	ds_read_b128 v[188:191], v241 offset:24000
	global_load_lds_dwordx4 v[198:199], off
	s_add_i32 m0, s69, 0x2200
	s_add_u32 s74, s40, 0xb0000
	v_lshl_add_u64 v[200:201], s[40:41], 0, v[210:211]
	s_addc_u32 s75, s41, 0
	s_add_i32 s69, s76, s33
	global_load_lds_dwordx4 v[200:201], off
	v_lshl_add_u64 v[216:217], s[74:75], 0, v[208:209]
	s_mov_b32 m0, s69
	v_lshl_add_u64 v[218:219], s[42:43], 0, v[210:211]
	global_load_lds_dwordx4 v[216:217], off
	v_lshl_add_u64 v[216:217], s[74:75], 0, v[210:211]
	s_add_i32 m0, s69, 0x2200
	s_nop 0
	global_load_lds_dwordx4 v[216:217], off
	v_lshl_add_u64 v[216:217], s[42:43], 0, v[208:209]
	s_mov_b32 m0, s0
	s_nop 0
	global_load_lds_dwordx4 v[216:217], off
	s_mov_b32 m0, s5
	s_nop 0
	global_load_lds_dwordx4 v[218:219], off
	s_waitcnt vmcnt(8)
	s_waitcnt lgkmcnt(0)
	s_barrier
; #define PG8_STAGE(bufoff, gbase, voff) do { _Pragma("unroll") for (int _i = 0; _i < 2; ++_i) \
;         __builtin_amdgcn_global_load_lds((const unsigned*)((const char*)(gbase) + (voff)[_i]), (PG8_LAS unsigned*)(lds + (bufoff) + ldsw + _i * (8 * USTR)), 16, 0, 0); } while (0)
; #define PG8_LDA(dst, b, h) do { _Pragma("unroll") for (int m = 0; m < 4; ++m) _Pragma("unroll") for (int k = 0; k < 2; ++k) dst[m][k] = *(const PG8_LAS bf16x8*)(lds + PG8_SA(b, h) + aoff + m * (2 * USTR) + k * 64); } while (0)
; #define PG8_LDB(dst, b, h) do { _Pragma("unroll") for (int n = 0; n < 2; ++n) _Pragma("unroll") for (int k = 0; k < 2; ++k) dst[n][k] = *(const PG8_LAS bf16x8*)(lds + PG8_SB(b, h) + boff + n * (2 * USTR) + k * 64); } while (0)
; #define PG8_MMA(ai, bj, At, Bt) do { __builtin_amdgcn_s_setprio(1); _Pragma("unroll") for (int m = 0; m < 4; ++m) _Pragma("unroll") for (int n = 0; n < 2; ++n) _Pragma("unroll") for (int k = 0; k < 2; ++k) \
;         acc[ai][bj][m][n] = __builtin_amdgcn_mfma_f32_16x16x32_bf16(Bt[n][k], At[m][k], acc[ai][bj][m][n], 0, 0, 0); __builtin_amdgcn_s_setprio(0); } while (0)
; #define PG8_WAIT_V(n) asm volatile("s_waitcnt vmcnt(" #n ")" ::: "memory")
; #define PG8_WAIT_L(n) asm volatile("s_waitcnt lgkmcnt(" #n ")" ::: "memory")
; #define PG8_BAR __builtin_amdgcn_s_barrier()
; #define PG8_SCHED __builtin_amdgcn_sched_barrier(0)
; template <class Epi, class Sched, bool ALIGN_EPI, bool SP2>
; __device__ __forceinline__ void gemm_phase(PG8_LAS unsigned char* lds, const Gemm g, const Sched& S, const Epi& E, int wid) {
;     ...
;             PG8_WAIT_V(8); PG8_WAIT_L(0); PG8_BAR; PG8_MMA(1, 0, At, B0); PG8_MMA(1, 1, At, B1); PG8_BAR; PG8_SCHED;
;             PG8_LDB(B0, 1, 0); PG8_LDB(B1, 1, 1); PG8_SCHED; PG8_LDA(At, 1, 0); PG8_STAGE(PG8_SA(0, 1), a2 + hstepA, voffA);
;             PG8_WAIT_V(8); PG8_WAIT_L(0); PG8_BAR; PG8_MMA(0, 0, At, B0); PG8_MMA(0, 1, At, B1); PG8_BAR; PG8_SCHED;
	s_setprio 1
	s_waitcnt lgkmcnt(0)
	v_mfma_f32_16x16x32_bf16 v[76:79], v[40:43], v[160:163], 0
	v_mfma_f32_16x16x32_bf16 v[72:75], v[48:51], v[160:163], 0
	v_mfma_f32_16x16x32_bf16 v[60:63], v[40:43], v[168:171], 0
	v_mfma_f32_16x16x32_bf16 v[56:59], v[48:51], v[168:171], 0
	v_mfma_f32_16x16x32_bf16 v[24:27], v[40:43], v[176:179], 0
	v_mfma_f32_16x16x32_bf16 v[28:31], v[48:51], v[176:179], 0
	v_mfma_f32_16x16x32_bf16 v[8:11], v[40:43], v[184:187], 0
	v_mfma_f32_16x16x32_bf16 v[12:15], v[48:51], v[184:187], 0
	v_mfma_f32_16x16x32_bf16 v[76:79], v[44:47], v[164:167], v[76:79]
	v_mfma_f32_16x16x32_bf16 v[72:75], v[52:55], v[164:167], v[72:75]
	v_mfma_f32_16x16x32_bf16 v[60:63], v[44:47], v[172:175], v[60:63]
	v_mfma_f32_16x16x32_bf16 v[56:59], v[52:55], v[172:175], v[56:59]
	v_mfma_f32_16x16x32_bf16 v[24:27], v[44:47], v[180:183], v[24:27]
	v_mfma_f32_16x16x32_bf16 v[28:31], v[52:55], v[180:183], v[28:31]
	v_mfma_f32_16x16x32_bf16 v[8:11], v[44:47], v[188:191], v[8:11]
	v_mfma_f32_16x16x32_bf16 v[12:15], v[52:55], v[188:191], v[12:15]
	s_setprio 0
	s_setprio 1
	v_mfma_f32_16x16x32_bf16 v[36:39], v[144:147], v[168:171], 0
	v_mfma_f32_16x16x32_bf16 v[32:35], v[152:155], v[168:171], 0
	v_mfma_f32_16x16x32_bf16 v[20:23], v[144:147], v[176:179], 0
	v_mfma_f32_16x16x32_bf16 v[16:19], v[152:155], v[176:179], 0
	v_mfma_f32_16x16x32_bf16 v[4:7], v[144:147], v[184:187], 0
	v_mfma_f32_16x16x32_bf16 v[0:3], v[152:155], v[184:187], 0
	v_mfma_f32_16x16x32_bf16 v[40:43], v[144:147], v[160:163], 0
	v_mfma_f32_16x16x32_bf16 v[44:47], v[152:155], v[160:163], 0
	v_mfma_f32_16x16x32_bf16 v[36:39], v[148:151], v[172:175], v[36:39]
	v_mfma_f32_16x16x32_bf16 v[32:35], v[156:159], v[172:175], v[32:35]
	v_mfma_f32_16x16x32_bf16 v[20:23], v[148:151], v[180:183], v[20:23]
	v_mfma_f32_16x16x32_bf16 v[16:19], v[156:159], v[180:183], v[16:19]
	v_mfma_f32_16x16x32_bf16 v[4:7], v[148:151], v[188:191], v[4:7]
	v_mfma_f32_16x16x32_bf16 v[0:3], v[156:159], v[188:191], v[0:3]
	v_mfma_f32_16x16x32_bf16 v[40:43], v[148:151], v[164:167], v[40:43]
	v_mfma_f32_16x16x32_bf16 v[44:47], v[156:159], v[164:167], v[44:47]
	s_setprio 0
	s_barrier
	s_add_i32 s69, 0, 0x19800
	s_add_i32 s74, 0, 0x1dc00
	v_add_u32_e32 v68, s69, v197
	v_add_u32_e32 v156, s74, v197
	ds_read_b128 v[48:51], v68
	ds_read_b128 v[52:55], v68 offset:64
	ds_read_b128 v[64:67], v68 offset:2176
	ds_read_b128 v[68:71], v68 offset:2240
	ds_read_b128 v[144:147], v156
	ds_read_b128 v[148:151], v156 offset:64
	ds_read_b128 v[152:155], v156 offset:2176
	ds_read_b128 v[156:159], v156 offset:2240
	s_add_u32 s42, s42, 0xb0000
	s_addc_u32 s43, s43, 0
	s_mov_b32 m0, s29
	v_lshl_add_u64 v[220:221], s[42:43], 0, v[208:209]
	ds_read_b128 v[160:163], v241 offset:34816
	ds_read_b128 v[164:167], v241 offset:34880
	ds_read_b128 v[168:171], v241 offset:36992
	ds_read_b128 v[172:175], v241 offset:37056
	ds_read_b128 v[176:179], v241 offset:39168
	ds_read_b128 v[180:183], v241 offset:39232
	ds_read_b128 v[184:187], v241 offset:41344
	ds_read_b128 v[188:191], v241 offset:41408
	global_load_lds_dwordx4 v[220:221], off
	v_lshl_add_u64 v[220:221], s[42:43], 0, v[210:211]
	s_mov_b32 m0, s56
	s_nop 0
	global_load_lds_dwordx4 v[220:221], off
	s_waitcnt vmcnt(8)
	s_waitcnt lgkmcnt(0)
	s_barrier
	s_setprio 1
	s_waitcnt lgkmcnt(0)
	v_mfma_f32_16x16x32_bf16 v[132:135], v[48:51], v[160:163], v[132:135]
	v_mfma_f32_16x16x32_bf16 v[128:131], v[64:67], v[160:163], v[128:131]
	v_mfma_f32_16x16x32_bf16 v[124:127], v[48:51], v[168:171], v[124:127]
	v_mfma_f32_16x16x32_bf16 v[120:123], v[64:67], v[168:171], v[120:123]
	v_mfma_f32_16x16x32_bf16 v[108:111], v[48:51], v[176:179], v[108:111]
	v_mfma_f32_16x16x32_bf16 v[104:107], v[64:67], v[176:179], v[104:107]
	v_mfma_f32_16x16x32_bf16 v[92:95], v[48:51], v[184:187], v[92:95]
	v_mfma_f32_16x16x32_bf16 v[88:91], v[64:67], v[184:187], v[88:91]
	v_mfma_f32_16x16x32_bf16 v[132:135], v[52:55], v[164:167], v[132:135]
	v_mfma_f32_16x16x32_bf16 v[128:131], v[68:71], v[164:167], v[128:131]
	v_mfma_f32_16x16x32_bf16 v[124:127], v[52:55], v[172:175], v[124:127]
	v_mfma_f32_16x16x32_bf16 v[120:123], v[68:71], v[172:175], v[120:123]
	v_mfma_f32_16x16x32_bf16 v[108:111], v[52:55], v[180:183], v[108:111]
	v_mfma_f32_16x16x32_bf16 v[104:107], v[68:71], v[180:183], v[104:107]
	v_mfma_f32_16x16x32_bf16 v[92:95], v[52:55], v[188:191], v[92:95]
	v_mfma_f32_16x16x32_bf16 v[88:91], v[68:71], v[188:191], v[88:91]
	s_setprio 0
	s_setprio 1
	v_mfma_f32_16x16x32_bf16 v[140:143], v[144:147], v[160:163], v[140:143]
	v_mfma_f32_16x16x32_bf16 v[136:139], v[152:155], v[160:163], v[136:139]
	v_mfma_f32_16x16x32_bf16 v[116:119], v[144:147], v[168:171], v[116:119]
	v_mfma_f32_16x16x32_bf16 v[112:115], v[152:155], v[168:171], v[112:115]
	v_mfma_f32_16x16x32_bf16 v[100:103], v[144:147], v[176:179], v[100:103]
	v_mfma_f32_16x16x32_bf16 v[96:99], v[152:155], v[176:179], v[96:99]
	v_mfma_f32_16x16x32_bf16 v[84:87], v[144:147], v[184:187], v[84:87]
	v_mfma_f32_16x16x32_bf16 v[80:83], v[152:155], v[184:187], v[80:83]
	v_mfma_f32_16x16x32_bf16 v[140:143], v[148:151], v[164:167], v[140:143]
	v_mfma_f32_16x16x32_bf16 v[136:139], v[156:159], v[164:167], v[136:139]
	v_mfma_f32_16x16x32_bf16 v[116:119], v[148:151], v[172:175], v[116:119]
	v_mfma_f32_16x16x32_bf16 v[112:115], v[156:159], v[172:175], v[112:115]
	v_mfma_f32_16x16x32_bf16 v[100:103], v[148:151], v[180:183], v[100:103]
	v_mfma_f32_16x16x32_bf16 v[96:99], v[156:159], v[180:183], v[96:99]
	v_mfma_f32_16x16x32_bf16 v[84:87], v[148:151], v[188:191], v[84:87]
	v_mfma_f32_16x16x32_bf16 v[80:83], v[156:159], v[188:191], v[80:83]
	s_setprio 0
	s_barrier
; #define PG8_STAGE(bufoff, gbase, voff) do { _Pragma("unroll") for (int _i = 0; _i < 2; ++_i) \
;         __builtin_amdgcn_global_load_lds((const unsigned*)((const char*)(gbase) + (voff)[_i]), (PG8_LAS unsigned*)(lds + (bufoff) + ldsw + _i * (8 * USTR)), 16, 0, 0); } while (0)
; #define PG8_LDA(dst, b, h) do { _Pragma("unroll") for (int m = 0; m < 4; ++m) _Pragma("unroll") for (int k = 0; k < 2; ++k) dst[m][k] = *(const PG8_LAS bf16x8*)(lds + PG8_SA(b, h) + aoff + m * (2 * USTR) + k * 64); } while (0)
; #define PG8_MMA(ai, bj, At, Bt) do { __builtin_amdgcn_s_setprio(1); _Pragma("unroll") for (int m = 0; m < 4; ++m) _Pragma("unroll") for (int n = 0; n < 2; ++n) _Pragma("unroll") for (int k = 0; k < 2; ++k) \
;         acc[ai][bj][m][n] = __builtin_amdgcn_mfma_f32_16x16x32_bf16(Bt[n][k], At[m][k], acc[ai][bj][m][n], 0, 0, 0); __builtin_amdgcn_s_setprio(0); } while (0)
; #define PG8_WAIT_V(n) asm volatile("s_waitcnt vmcnt(" #n ")" ::: "memory")
; #define PG8_WAIT_L(n) asm volatile("s_waitcnt lgkmcnt(" #n ")" ::: "memory")
; #define PG8_BAR __builtin_amdgcn_s_barrier()
; #define PG8_SCHED __builtin_amdgcn_sched_barrier(0)
; template <class Epi, class Sched, bool ALIGN_EPI, bool SP2>
; __device__ __forceinline__ void gemm_phase(PG8_LAS unsigned char* lds, const Gemm g, const Sched& S, const Epi& E, int wid) {
;     ...
;             PG8_LDA(At, 1, 1); PG8_STAGE(PG8_SB(1, 0), b3, voffB); PG8_STAGE(PG8_SB(1, 1), b3 + hstepB, voffB); PG8_STAGE(PG8_SA(1, 0), a3, voffA);
;             PG8_WAIT_V(8); PG8_WAIT_L(0); PG8_BAR; PG8_MMA(1, 0, At, B0); PG8_MMA(1, 1, At, B1); PG8_BAR; PG8_SCHED;
	s_add_i32 s42, s69, s33
	v_lshl_add_u64 v[198:199], v[198:199], 0, s[6:7]
	s_mov_b32 m0, s42
	ds_read_b128 v[160:163], v241 offset:52224
	ds_read_b128 v[164:167], v241 offset:52288
	ds_read_b128 v[168:171], v241 offset:54400
	ds_read_b128 v[172:175], v241 offset:54464
	ds_read_b128 v[176:179], v241 offset:56576
	ds_read_b128 v[180:183], v241 offset:56640
	ds_read_b128 v[184:187], v241 offset:58752
	ds_read_b128 v[188:191], v241 offset:58816
	global_load_lds_dwordx4 v[198:199], off
	s_add_i32 m0, s42, 0x2200
	s_add_u32 s40, s40, 0xb0080
	v_lshl_add_u64 v[198:199], v[200:201], 0, s[6:7]
	s_addc_u32 s41, s41, 0
	s_add_i32 s42, s74, s33
	global_load_lds_dwordx4 v[198:199], off
	v_lshl_add_u64 v[198:199], s[40:41], 0, v[208:209]
	s_mov_b32 m0, s42
	s_nop 0
	global_load_lds_dwordx4 v[198:199], off
	v_lshl_add_u64 v[198:199], s[40:41], 0, v[210:211]
	s_add_i32 m0, s42, 0x2200
	s_nop 0
	global_load_lds_dwordx4 v[198:199], off
	v_lshl_add_u64 v[198:199], v[216:217], 0, s[6:7]
	s_mov_b32 m0, s57
	s_nop 0
	global_load_lds_dwordx4 v[198:199], off
	v_lshl_add_u64 v[198:199], v[218:219], 0, s[6:7]
	s_mov_b32 m0, s70
	s_nop 0
	global_load_lds_dwordx4 v[198:199], off
	s_waitcnt vmcnt(8)
	s_waitcnt lgkmcnt(0)
	s_barrier
	s_setprio 1
	s_waitcnt lgkmcnt(0)
	v_mfma_f32_16x16x32_bf16 v[76:79], v[48:51], v[160:163], v[76:79]
	v_mfma_f32_16x16x32_bf16 v[72:75], v[64:67], v[160:163], v[72:75]
	v_mfma_f32_16x16x32_bf16 v[60:63], v[48:51], v[168:171], v[60:63]
	v_mfma_f32_16x16x32_bf16 v[56:59], v[64:67], v[168:171], v[56:59]
	v_mfma_f32_16x16x32_bf16 v[24:27], v[48:51], v[176:179], v[24:27]
	v_mfma_f32_16x16x32_bf16 v[28:31], v[64:67], v[176:179], v[28:31]
	v_mfma_f32_16x16x32_bf16 v[8:11], v[48:51], v[184:187], v[8:11]
	v_mfma_f32_16x16x32_bf16 v[12:15], v[64:67], v[184:187], v[12:15]
	v_mfma_f32_16x16x32_bf16 v[76:79], v[52:55], v[164:167], v[76:79]
	v_mfma_f32_16x16x32_bf16 v[72:75], v[68:71], v[164:167], v[72:75]
	v_mfma_f32_16x16x32_bf16 v[60:63], v[52:55], v[172:175], v[60:63]
	v_mfma_f32_16x16x32_bf16 v[56:59], v[68:71], v[172:175], v[56:59]
	v_mfma_f32_16x16x32_bf16 v[24:27], v[52:55], v[180:183], v[24:27]
	v_mfma_f32_16x16x32_bf16 v[28:31], v[68:71], v[180:183], v[28:31]
	v_mfma_f32_16x16x32_bf16 v[8:11], v[52:55], v[188:191], v[8:11]
	v_mfma_f32_16x16x32_bf16 v[12:15], v[68:71], v[188:191], v[12:15]
	s_setprio 0
	s_setprio 1
	v_mfma_f32_16x16x32_bf16 v[40:43], v[144:147], v[160:163], v[40:43]
	v_mfma_f32_16x16x32_bf16 v[68:71], v[148:151], v[164:167], v[40:43]
	v_mfma_f32_16x16x32_bf16 v[40:43], v[152:155], v[160:163], v[44:47]
	v_mfma_f32_16x16x32_bf16 v[36:39], v[144:147], v[168:171], v[36:39]
	v_mfma_f32_16x16x32_bf16 v[32:35], v[152:155], v[168:171], v[32:35]
	v_mfma_f32_16x16x32_bf16 v[20:23], v[144:147], v[176:179], v[20:23]
	v_mfma_f32_16x16x32_bf16 v[16:19], v[152:155], v[176:179], v[16:19]
	v_mfma_f32_16x16x32_bf16 v[4:7], v[144:147], v[184:187], v[4:7]
	v_mfma_f32_16x16x32_bf16 v[0:3], v[152:155], v[184:187], v[0:3]
	v_mfma_f32_16x16x32_bf16 v[64:67], v[156:159], v[164:167], v[40:43]
	v_mfma_f32_16x16x32_bf16 v[36:39], v[148:151], v[172:175], v[36:39]
	v_mfma_f32_16x16x32_bf16 v[32:35], v[156:159], v[172:175], v[32:35]
	v_mfma_f32_16x16x32_bf16 v[20:23], v[148:151], v[180:183], v[20:23]
	v_mfma_f32_16x16x32_bf16 v[16:19], v[156:159], v[180:183], v[16:19]
	v_mfma_f32_16x16x32_bf16 v[4:7], v[148:151], v[188:191], v[4:7]
	v_mfma_f32_16x16x32_bf16 v[0:3], v[156:159], v[188:191], v[0:3]
	s_setprio 0
	s_barrier
	s_add_i32 s68, s68, 2
	s_add_u32 s38, s38, 0x100
	s_addc_u32 s39, s39, 0
	s_add_u32 s26, s26, 0x100
	s_addc_u32 s27, s27, 0
	s_cmp_gt_u32 s68, 41

; #define PG8_LAS __attribute__((address_space(3)))
; #define PG8_STAGE(bufoff, gbase, voff) do { _Pragma("unroll") for (int _i = 0; _i < 2; ++_i) \
;         __builtin_amdgcn_global_load_lds((const unsigned*)((const char*)(gbase) + (voff)[_i]), (PG8_LAS unsigned*)(lds + (bufoff) + ldsw + _i * (8 * USTR)), 16, 0, 0); } while (0)
; #define PG8_WAIT_V(n) asm volatile("s_waitcnt vmcnt(" #n ")" ::: "memory")
; #define PG8_WAIT_L(n) asm volatile("s_waitcnt lgkmcnt(" #n ")" ::: "memory")
; #define PG8_BAR __builtin_amdgcn_s_barrier()
; template <class Epi, class Sched, bool ALIGN_EPI, bool SP2>
; __device__ __forceinline__ void gemm_phase(PG8_LAS unsigned char* lds, const Gemm g, const Sched& S, const Epi& E, int wid) {
;     ...
;         const bool has_next = S.next(ui + 1, nxt);
;         const char* nA = has_next ? (const char*)g.A + (size_t)nxt.pm * tstepA : cA; const char* nB = has_next ? (const char*)g.Bt + (size_t)nxt.pn * tstepB : cB;
;         for (int t = 0; t < nt; t += 2) {
;             const bool last = (t == nt - 2);
;             const char* a1 = cA + (size_t)(t + 1) * kstep;
;             const char* a2 = last ? nA : cA + (size_t)(t + 2) * kstep; const char* b2 = last ? nB : cB + (size_t)(t + 2) * kstep;
;             const char* a3 = a2 + kstep; const char* b3 = b2 + kstep;
;             if constexpr (Epi::PRE == 1) { if (last) {
;                 const char* rsrc; const char* ssrc; E.pre(cur, rsrc, ssrc);
; #pragma unroll
;                 for (int _i = 0; _i < 2; ++_i) __builtin_amdgcn_global_load_lds((const unsigned*)(rsrc + (wid + 8 * _i) * 1024 + lane * 16), (PG8_LAS unsigned*)(lds + LDS_XOFF + (wid + 8 * _i) * 1024), 16, 0, 0);
;                 if (wid == 0) __builtin_amdgcn_global_load_lds((const unsigned*)(ssrc + lane * 16), (PG8_LAS unsigned*)(lds + LDS_XOFF + 16384), 16, 0, 0);
;             } }
;             if constexpr (SP2) {
;             PG8_LDB(B0, 0, 0); PG8_LDB(B1, 0, 1); PG8_SCHED; PG8_LDA(At, 0, 0); PG8_STAGE(PG8_SA(1, 1), a1 + hstepA, voffA);
;             PG8_WAIT_V(8); PG8_WAIT_L(0); PG8_BAR; PG8_MMA(0, 0, At, B0); PG8_MMA(0, 1, At, B1); PG8_BAR; PG8_SCHED;
;             PG8_LDA(At, 0, 1); PG8_STAGE(PG8_SB(0, 0), b2, voffB); PG8_STAGE(PG8_SB(0, 1), b2 + hstepB, voffB); PG8_STAGE(PG8_SA(0, 0), a2, voffA);
;             PG8_WAIT_V(8); PG8_WAIT_L(0); PG8_BAR; PG8_MMA(1, 0, At, B0); PG8_MMA(1, 1, At, B1); PG8_BAR; PG8_SCHED;
.LBB0_372:
	s_ashr_i32 s41, s40, 31
	s_lshl_b64 s[26:27], s[40:41], 19
	v_readlane_b32 s23, v255, 2
	s_add_u32 s42, s23, s26
	v_readlane_b32 s23, v255, 3
	s_addc_u32 s43, s23, s27
	s_and_b64 s[26:27], s[36:37], exec
	s_cselect_b32 s26, s43, s39
	s_cselect_b32 s27, s42, s38
	s_ashr_i32 s23, s22, 31
	s_lshl_b64 s[44:45], s[22:23], 19
	v_readlane_b32 s23, v254, 62
	s_add_u32 s44, s23, s44
	v_readlane_b32 s23, v254, 63
	s_addc_u32 s45, s23, s45
	s_and_b64 s[74:75], s[36:37], exec
	s_cselect_b32 s41, s45, s69
	s_cselect_b32 s73, s44, s68
	s_lshl_b32 s23, s70, 8
	s_lshl_b32 s70, s2, 8
	s_ashr_i32 s71, s70, 31
	v_readlane_b32 s46, v254, 49
	v_lshl_add_u64 v[0:1], s[70:71], 2, v[152:153]
	s_add_i32 s70, s23, s46
	s_ashr_i32 s71, s70, 31
	s_lshl_b64 s[74:75], s[70:71], 6
	v_lshl_add_u64 v[2:3], v[150:151], 0, s[74:75]
	s_add_i32 s74, s70, 0xffff8000
	s_lshr_b32 s74, s74, 14
	s_ashr_i32 s71, s70, 12
	s_add_i32 s74, s74, 8
	s_cmp_lt_i32 s70, 0x8000
	s_cselect_b32 s70, s71, s74
	s_add_u32 s38, s38, 0x40080
	v_readlane_b32 s46, v252, 20
	s_addc_u32 s39, s39, 0
	v_readlane_b32 s47, v252, 21
	v_mad_i64_i32 v[84:85], s[70:71], s70, v240, v[0:1]
	s_add_u32 s74, s68, 0x100
	v_lshl_add_u64 v[80:81], v[2:3], 0, s[18:19]
	v_lshl_add_u64 v[82:83], v[2:3], 0, s[46:47]
	s_addc_u32 s75, s69, 0
	s_mov_b32 s76, -2
	s_cmp_eq_u32 s76, 12
	s_cselect_b64 s[68:69], -1, 0
	s_add_u32 s70, s38, 0xfffc0080
	s_addc_u32 s71, s39, -1
	s_and_b64 s[68:69], s[68:69], exec
	s_cselect_b32 s71, s26, s71
	s_cselect_b32 s70, s27, s70
	s_cselect_b32 s69, s41, s75
	s_cselect_b32 s68, s73, s74
	s_add_i32 s77, 0, 0x11000
	v_add_u32_e32 v94, s77, v161
	s_add_i32 s89, 0, 0x15400
	ds_read_b128 v[86:89], v94
	ds_read_b128 v[90:93], v94 offset:64
	ds_read_b128 v[164:167], v94 offset:2176
	ds_read_b128 v[168:171], v94 offset:2240
	v_add_u32_e32 v94, s89, v161
	ds_read_b128 v[172:175], v94
	ds_read_b128 v[176:179], v94 offset:64
	ds_read_b128 v[180:183], v94 offset:2176
	ds_read_b128 v[184:187], v94 offset:2240
	v_lshl_add_u64 v[94:95], s[38:39], 0, v[154:155]
	s_add_i32 m0, s0, 0xcc00
	ds_read_b128 v[188:191], v163
	ds_read_b128 v[208:211], v163 offset:64
	ds_read_b128 v[212:215], v163 offset:2176
	ds_read_b128 v[216:219], v163 offset:2240
	ds_read_b128 v[220:223], v163 offset:4352
	ds_read_b128 v[224:227], v163 offset:4416
	ds_read_b128 v[228:231], v163 offset:6528
	ds_read_b128 v[242:245], v163 offset:6592
	global_load_lds_dwordx4 v[94:95], off
	v_lshl_add_u64 v[94:95], s[38:39], 0, v[156:157]
	s_add_i32 m0, s0, 0xee00
	s_nop 0
	global_load_lds_dwordx4 v[94:95], off
	s_waitcnt vmcnt(8)
	s_waitcnt lgkmcnt(0)
	s_barrier
	s_setprio 1
	s_waitcnt lgkmcnt(0)
	v_mfma_f32_16x16x32_bf16 v[140:143], v[86:89], v[188:191], 0
	v_mfma_f32_16x16x32_bf16 v[136:139], v[164:167], v[188:191], 0
	v_mfma_f32_16x16x32_bf16 v[124:127], v[86:89], v[212:215], 0
	v_mfma_f32_16x16x32_bf16 v[120:123], v[164:167], v[212:215], 0
	v_mfma_f32_16x16x32_bf16 v[108:111], v[86:89], v[220:223], 0
	v_mfma_f32_16x16x32_bf16 v[104:107], v[164:167], v[220:223], 0
	v_mfma_f32_16x16x32_bf16 v[76:79], v[86:89], v[228:231], 0
	v_mfma_f32_16x16x32_bf16 v[72:75], v[164:167], v[228:231], 0
	v_mfma_f32_16x16x32_bf16 v[140:143], v[90:93], v[208:211], v[140:143]
	v_mfma_f32_16x16x32_bf16 v[136:139], v[168:171], v[208:211], v[136:139]
	v_mfma_f32_16x16x32_bf16 v[124:127], v[90:93], v[216:219], v[124:127]
	v_mfma_f32_16x16x32_bf16 v[120:123], v[168:171], v[216:219], v[120:123]
	v_mfma_f32_16x16x32_bf16 v[108:111], v[90:93], v[224:227], v[108:111]
	v_mfma_f32_16x16x32_bf16 v[104:107], v[168:171], v[224:227], v[104:107]
	v_mfma_f32_16x16x32_bf16 v[76:79], v[90:93], v[242:245], v[76:79]
	v_mfma_f32_16x16x32_bf16 v[72:75], v[168:171], v[242:245], v[72:75]
	s_setprio 0
	s_setprio 1
	v_mfma_f32_16x16x32_bf16 v[132:135], v[172:175], v[188:191], 0
	v_mfma_f32_16x16x32_bf16 v[128:131], v[180:183], v[188:191], 0
	v_mfma_f32_16x16x32_bf16 v[116:119], v[172:175], v[212:215], 0
	v_mfma_f32_16x16x32_bf16 v[112:115], v[180:183], v[212:215], 0
	v_mfma_f32_16x16x32_bf16 v[100:103], v[172:175], v[220:223], 0
	v_mfma_f32_16x16x32_bf16 v[94:97], v[180:183], v[220:223], 0
	v_mfma_f32_16x16x32_bf16 v[68:71], v[172:175], v[228:231], 0
	v_mfma_f32_16x16x32_bf16 v[64:67], v[180:183], v[228:231], 0
	v_mfma_f32_16x16x32_bf16 v[132:135], v[176:179], v[208:211], v[132:135]
	v_mfma_f32_16x16x32_bf16 v[128:131], v[184:187], v[208:211], v[128:131]
	v_mfma_f32_16x16x32_bf16 v[116:119], v[176:179], v[216:219], v[116:119]
	v_mfma_f32_16x16x32_bf16 v[112:115], v[184:187], v[216:219], v[112:115]
	v_mfma_f32_16x16x32_bf16 v[100:103], v[176:179], v[224:227], v[100:103]
	v_mfma_f32_16x16x32_bf16 v[94:97], v[184:187], v[224:227], v[94:97]
	v_mfma_f32_16x16x32_bf16 v[68:71], v[176:179], v[242:245], v[68:71]
	v_mfma_f32_16x16x32_bf16 v[64:67], v[184:187], v[242:245], v[64:67]
	s_setprio 0
	s_barrier
	s_add_i32 s77, s77, s33
	v_lshl_add_u64 v[158:159], s[68:69], 0, v[192:193]
	s_mov_b32 m0, s77
	ds_read_b128 v[188:191], v163 offset:17408
	ds_read_b128 v[208:211], v163 offset:17472
	ds_read_b128 v[212:215], v163 offset:19584
	ds_read_b128 v[216:219], v163 offset:19648
	ds_read_b128 v[220:223], v163 offset:21760
	ds_read_b128 v[224:227], v163 offset:21824
	ds_read_b128 v[228:231], v163 offset:23936
	ds_read_b128 v[242:245], v163 offset:24000
	global_load_lds_dwordx4 v[158:159], off
	s_add_i32 m0, s77, 0x2200
	s_add_u32 s78, s68, 0x40000
	v_lshl_add_u64 v[198:199], s[68:69], 0, v[144:145]
	s_addc_u32 s79, s69, 0
	s_add_i32 s77, s89, s33
	global_load_lds_dwordx4 v[198:199], off
	v_lshl_add_u64 v[98:99], s[78:79], 0, v[192:193]
	s_mov_b32 m0, s77
	v_lshl_add_u64 v[200:201], s[70:71], 0, v[148:149]
	global_load_lds_dwordx4 v[98:99], off
	v_lshl_add_u64 v[98:99], s[78:79], 0, v[144:145]
	s_add_i32 m0, s77, 0x2200
	v_lshl_add_u64 v[232:233], s[70:71], 0, v[146:147]
	global_load_lds_dwordx4 v[98:99], off
	s_mov_b32 m0, s0
	s_nop 0
	global_load_lds_dwordx4 v[200:201], off
	s_mov_b32 m0, s5
	s_nop 0
	global_load_lds_dwordx4 v[232:233], off
	s_waitcnt vmcnt(8)
	s_waitcnt lgkmcnt(0)
	s_barrier
; #define PG8_STAGE(bufoff, gbase, voff) do { _Pragma("unroll") for (int _i = 0; _i < 2; ++_i) \
;         __builtin_amdgcn_global_load_lds((const unsigned*)((const char*)(gbase) + (voff)[_i]), (PG8_LAS unsigned*)(lds + (bufoff) + ldsw + _i * (8 * USTR)), 16, 0, 0); } while (0)
; #define PG8_LDA(dst, b, h) do { _Pragma("unroll") for (int m = 0; m < 4; ++m) _Pragma("unroll") for (int k = 0; k < 2; ++k) dst[m][k] = *(const PG8_LAS bf16x8*)(lds + PG8_SA(b, h) + aoff + m * (2 * USTR) + k * 64); } while (0)
; #define PG8_LDB(dst, b, h) do { _Pragma("unroll") for (int n = 0; n < 2; ++n) _Pragma("unroll") for (int k = 0; k < 2; ++k) dst[n][k] = *(const PG8_LAS bf16x8*)(lds + PG8_SB(b, h) + boff + n * (2 * USTR) + k * 64); } while (0)
; #define PG8_MMA(ai, bj, At, Bt) do { __builtin_amdgcn_s_setprio(1); _Pragma("unroll") for (int m = 0; m < 4; ++m) _Pragma("unroll") for (int n = 0; n < 2; ++n) _Pragma("unroll") for (int k = 0; k < 2; ++k) \
;         acc[ai][bj][m][n] = __builtin_amdgcn_mfma_f32_16x16x32_bf16(Bt[n][k], At[m][k], acc[ai][bj][m][n], 0, 0, 0); __builtin_amdgcn_s_setprio(0); } while (0)
; #define PG8_WAIT_V(n) asm volatile("s_waitcnt vmcnt(" #n ")" ::: "memory")
; #define PG8_WAIT_L(n) asm volatile("s_waitcnt lgkmcnt(" #n ")" ::: "memory")
; #define PG8_BAR __builtin_amdgcn_s_barrier()
; #define PG8_SCHED __builtin_amdgcn_sched_barrier(0)
; template <class Epi, class Sched, bool ALIGN_EPI, bool SP2>
; __device__ __forceinline__ void gemm_phase(PG8_LAS unsigned char* lds, const Gemm g, const Sched& S, const Epi& E, int wid) {
;     ...
;             PG8_WAIT_V(8); PG8_WAIT_L(0); PG8_BAR; PG8_MMA(1, 0, At, B0); PG8_MMA(1, 1, At, B1); PG8_BAR; PG8_SCHED;
;             PG8_LDB(B0, 1, 0); PG8_LDB(B1, 1, 1); PG8_SCHED; PG8_LDA(At, 1, 0); PG8_STAGE(PG8_SA(0, 1), a2 + hstepA, voffA);
;             PG8_WAIT_V(8); PG8_WAIT_L(0); PG8_BAR; PG8_MMA(0, 0, At, B0); PG8_MMA(0, 1, At, B1); PG8_BAR; PG8_SCHED;
	s_setprio 1
	s_waitcnt lgkmcnt(0)
	v_mfma_f32_16x16x32_bf16 v[60:63], v[86:89], v[188:191], 0
	v_mfma_f32_16x16x32_bf16 v[56:59], v[164:167], v[188:191], 0
	v_mfma_f32_16x16x32_bf16 v[44:47], v[86:89], v[212:215], 0
	v_mfma_f32_16x16x32_bf16 v[40:43], v[164:167], v[212:215], 0
	v_mfma_f32_16x16x32_bf16 v[28:31], v[86:89], v[220:223], 0
	v_mfma_f32_16x16x32_bf16 v[24:27], v[164:167], v[220:223], 0
	v_mfma_f32_16x16x32_bf16 v[12:15], v[86:89], v[228:231], 0
	v_mfma_f32_16x16x32_bf16 v[8:11], v[164:167], v[228:231], 0
	v_mfma_f32_16x16x32_bf16 v[60:63], v[90:93], v[208:211], v[60:63]
	v_mfma_f32_16x16x32_bf16 v[56:59], v[168:171], v[208:211], v[56:59]
	v_mfma_f32_16x16x32_bf16 v[44:47], v[90:93], v[216:219], v[44:47]
	v_mfma_f32_16x16x32_bf16 v[40:43], v[168:171], v[216:219], v[40:43]
	v_mfma_f32_16x16x32_bf16 v[28:31], v[90:93], v[224:227], v[28:31]
	v_mfma_f32_16x16x32_bf16 v[24:27], v[168:171], v[224:227], v[24:27]
	v_mfma_f32_16x16x32_bf16 v[12:15], v[90:93], v[242:245], v[12:15]
	v_mfma_f32_16x16x32_bf16 v[8:11], v[168:171], v[242:245], v[8:11]
	s_setprio 0
	s_setprio 1
	v_mfma_f32_16x16x32_bf16 v[52:55], v[172:175], v[188:191], 0
	v_mfma_f32_16x16x32_bf16 v[48:51], v[180:183], v[188:191], 0
	v_mfma_f32_16x16x32_bf16 v[36:39], v[172:175], v[212:215], 0
	v_mfma_f32_16x16x32_bf16 v[32:35], v[180:183], v[212:215], 0
	v_mfma_f32_16x16x32_bf16 v[20:23], v[172:175], v[220:223], 0
	v_mfma_f32_16x16x32_bf16 v[16:19], v[180:183], v[220:223], 0
	v_mfma_f32_16x16x32_bf16 v[4:7], v[172:175], v[228:231], 0
	v_mfma_f32_16x16x32_bf16 v[0:3], v[180:183], v[228:231], 0
	v_mfma_f32_16x16x32_bf16 v[52:55], v[176:179], v[208:211], v[52:55]
	v_mfma_f32_16x16x32_bf16 v[48:51], v[184:187], v[208:211], v[48:51]
	v_mfma_f32_16x16x32_bf16 v[36:39], v[176:179], v[216:219], v[36:39]
	v_mfma_f32_16x16x32_bf16 v[32:35], v[184:187], v[216:219], v[32:35]
	v_mfma_f32_16x16x32_bf16 v[20:23], v[176:179], v[224:227], v[20:23]
	v_mfma_f32_16x16x32_bf16 v[16:19], v[184:187], v[224:227], v[16:19]
	v_mfma_f32_16x16x32_bf16 v[4:7], v[176:179], v[242:245], v[4:7]
	v_mfma_f32_16x16x32_bf16 v[0:3], v[184:187], v[242:245], v[0:3]
	s_setprio 0
	s_barrier
	s_add_i32 s77, 0, 0x19800
	v_add_u32_e32 v98, s77, v161
	s_add_i32 s78, 0, 0x1dc00
	ds_read_b128 v[86:89], v98
	ds_read_b128 v[90:93], v98 offset:64
	ds_read_b128 v[164:167], v98 offset:2176
	ds_read_b128 v[168:171], v98 offset:2240
	v_add_u32_e32 v98, s78, v161
	ds_read_b128 v[172:175], v98
	ds_read_b128 v[176:179], v98 offset:64
	ds_read_b128 v[180:183], v98 offset:2176
	ds_read_b128 v[184:187], v98 offset:2240
	s_add_u32 s70, s70, 0x40000
	s_addc_u32 s71, s71, 0
	s_mov_b32 m0, s10
	v_lshl_add_u64 v[98:99], s[70:71], 0, v[148:149]
	ds_read_b128 v[188:191], v163 offset:34816
	ds_read_b128 v[208:211], v163 offset:34880
	ds_read_b128 v[212:215], v163 offset:36992
	ds_read_b128 v[216:219], v163 offset:37056
	ds_read_b128 v[220:223], v163 offset:39168
	ds_read_b128 v[224:227], v163 offset:39232
	ds_read_b128 v[228:231], v163 offset:41344
	ds_read_b128 v[242:245], v163 offset:41408
	global_load_lds_dwordx4 v[98:99], off
	v_lshl_add_u64 v[98:99], s[70:71], 0, v[146:147]
	s_mov_b32 m0, s29
	s_nop 0
	global_load_lds_dwordx4 v[98:99], off
	s_waitcnt vmcnt(8)
	s_waitcnt lgkmcnt(0)
	s_barrier
	s_setprio 1
	s_waitcnt lgkmcnt(0)
	v_mfma_f32_16x16x32_bf16 v[140:143], v[86:89], v[188:191], v[140:143]
	v_mfma_f32_16x16x32_bf16 v[136:139], v[164:167], v[188:191], v[136:139]
	v_mfma_f32_16x16x32_bf16 v[124:127], v[86:89], v[212:215], v[124:127]
	v_mfma_f32_16x16x32_bf16 v[120:123], v[164:167], v[212:215], v[120:123]
	v_mfma_f32_16x16x32_bf16 v[108:111], v[86:89], v[220:223], v[108:111]
	v_mfma_f32_16x16x32_bf16 v[104:107], v[164:167], v[220:223], v[104:107]
	v_mfma_f32_16x16x32_bf16 v[76:79], v[86:89], v[228:231], v[76:79]
	v_mfma_f32_16x16x32_bf16 v[72:75], v[164:167], v[228:231], v[72:75]
	v_mfma_f32_16x16x32_bf16 v[140:143], v[90:93], v[208:211], v[140:143]
	v_mfma_f32_16x16x32_bf16 v[136:139], v[168:171], v[208:211], v[136:139]
	v_mfma_f32_16x16x32_bf16 v[124:127], v[90:93], v[216:219], v[124:127]
	v_mfma_f32_16x16x32_bf16 v[120:123], v[168:171], v[216:219], v[120:123]
	v_mfma_f32_16x16x32_bf16 v[108:111], v[90:93], v[224:227], v[108:111]
	v_mfma_f32_16x16x32_bf16 v[104:107], v[168:171], v[224:227], v[104:107]
	v_mfma_f32_16x16x32_bf16 v[76:79], v[90:93], v[242:245], v[76:79]
	v_mfma_f32_16x16x32_bf16 v[72:75], v[168:171], v[242:245], v[72:75]
	s_setprio 0
	s_setprio 1
	v_mfma_f32_16x16x32_bf16 v[132:135], v[172:175], v[188:191], v[132:135]
	v_mfma_f32_16x16x32_bf16 v[128:131], v[180:183], v[188:191], v[128:131]
	v_mfma_f32_16x16x32_bf16 v[116:119], v[172:175], v[212:215], v[116:119]
	v_mfma_f32_16x16x32_bf16 v[112:115], v[180:183], v[212:215], v[112:115]
	v_mfma_f32_16x16x32_bf16 v[98:101], v[172:175], v[220:223], v[100:103]
	v_mfma_f32_16x16x32_bf16 v[94:97], v[180:183], v[220:223], v[94:97]
	v_mfma_f32_16x16x32_bf16 v[68:71], v[172:175], v[228:231], v[68:71]
	v_mfma_f32_16x16x32_bf16 v[64:67], v[180:183], v[228:231], v[64:67]
	v_mfma_f32_16x16x32_bf16 v[132:135], v[176:179], v[208:211], v[132:135]
	v_mfma_f32_16x16x32_bf16 v[128:131], v[184:187], v[208:211], v[128:131]
	v_mfma_f32_16x16x32_bf16 v[116:119], v[176:179], v[216:219], v[116:119]
	v_mfma_f32_16x16x32_bf16 v[112:115], v[184:187], v[216:219], v[112:115]
	v_mfma_f32_16x16x32_bf16 v[100:103], v[176:179], v[224:227], v[98:101]
	v_mfma_f32_16x16x32_bf16 v[96:99], v[184:187], v[224:227], v[94:97]
	v_mfma_f32_16x16x32_bf16 v[68:71], v[176:179], v[242:245], v[68:71]
	v_mfma_f32_16x16x32_bf16 v[64:67], v[184:187], v[242:245], v[64:67]
	s_setprio 0
	s_barrier
; #define PG8_STAGE(bufoff, gbase, voff) do { _Pragma("unroll") for (int _i = 0; _i < 2; ++_i) \
;         __builtin_amdgcn_global_load_lds((const unsigned*)((const char*)(gbase) + (voff)[_i]), (PG8_LAS unsigned*)(lds + (bufoff) + ldsw + _i * (8 * USTR)), 16, 0, 0); } while (0)
; #define PG8_LDA(dst, b, h) do { _Pragma("unroll") for (int m = 0; m < 4; ++m) _Pragma("unroll") for (int k = 0; k < 2; ++k) dst[m][k] = *(const PG8_LAS bf16x8*)(lds + PG8_SA(b, h) + aoff + m * (2 * USTR) + k * 64); } while (0)
; #define PG8_MMA(ai, bj, At, Bt) do { __builtin_amdgcn_s_setprio(1); _Pragma("unroll") for (int m = 0; m < 4; ++m) _Pragma("unroll") for (int n = 0; n < 2; ++n) _Pragma("unroll") for (int k = 0; k < 2; ++k) \
;         acc[ai][bj][m][n] = __builtin_amdgcn_mfma_f32_16x16x32_bf16(Bt[n][k], At[m][k], acc[ai][bj][m][n], 0, 0, 0); __builtin_amdgcn_s_setprio(0); } while (0)
; #define PG8_WAIT_V(n) asm volatile("s_waitcnt vmcnt(" #n ")" ::: "memory")
; #define PG8_WAIT_L(n) asm volatile("s_waitcnt lgkmcnt(" #n ")" ::: "memory")
; #define PG8_BAR __builtin_amdgcn_s_barrier()
; #define PG8_SCHED __builtin_amdgcn_sched_barrier(0)
; template <class Epi, class Sched, bool ALIGN_EPI, bool SP2>
; __device__ __forceinline__ void gemm_phase(PG8_LAS unsigned char* lds, const Gemm g, const Sched& S, const Epi& E, int wid) {
;     ...
;             PG8_LDA(At, 1, 1); PG8_STAGE(PG8_SB(1, 0), b3, voffB); PG8_STAGE(PG8_SB(1, 1), b3 + hstepB, voffB); PG8_STAGE(PG8_SA(1, 0), a3, voffA);
;             PG8_WAIT_V(8); PG8_WAIT_L(0); PG8_BAR; PG8_MMA(1, 0, At, B0); PG8_MMA(1, 1, At, B1); PG8_BAR; PG8_SCHED;
	s_add_i32 s70, s77, s33
	v_lshl_add_u64 v[94:95], v[158:159], 0, s[6:7]
	s_mov_b32 m0, s70
	ds_read_b128 v[188:191], v163 offset:52224
	ds_read_b128 v[208:211], v163 offset:52288
	ds_read_b128 v[212:215], v163 offset:54400
	ds_read_b128 v[216:219], v163 offset:54464
	ds_read_b128 v[220:223], v163 offset:56576
	ds_read_b128 v[224:227], v163 offset:56640
	ds_read_b128 v[228:231], v163 offset:58752
	ds_read_b128 v[242:245], v163 offset:58816
	global_load_lds_dwordx4 v[94:95], off
	s_add_i32 m0, s70, 0x2200
	s_add_u32 s68, s68, 0x40080
	v_lshl_add_u64 v[94:95], v[198:199], 0, s[6:7]
	s_addc_u32 s69, s69, 0
	s_add_i32 s70, s78, s33
	global_load_lds_dwordx4 v[94:95], off
	v_lshl_add_u64 v[94:95], s[68:69], 0, v[192:193]
	s_mov_b32 m0, s70
	s_nop 0
	global_load_lds_dwordx4 v[94:95], off
	v_lshl_add_u64 v[94:95], s[68:69], 0, v[144:145]
	s_add_i32 m0, s70, 0x2200
	s_nop 0
	global_load_lds_dwordx4 v[94:95], off
	v_lshl_add_u64 v[94:95], v[200:201], 0, s[6:7]
	s_mov_b32 m0, s56
	s_nop 0
	global_load_lds_dwordx4 v[94:95], off
	v_lshl_add_u64 v[94:95], v[232:233], 0, s[6:7]
	s_mov_b32 m0, s57
	s_nop 0
	global_load_lds_dwordx4 v[94:95], off
	s_waitcnt vmcnt(8)
	s_waitcnt lgkmcnt(0)
	s_barrier
	s_setprio 1
	s_waitcnt lgkmcnt(0)
	v_mfma_f32_16x16x32_bf16 v[60:63], v[86:89], v[188:191], v[60:63]
	v_mfma_f32_16x16x32_bf16 v[56:59], v[164:167], v[188:191], v[56:59]
	v_mfma_f32_16x16x32_bf16 v[44:47], v[86:89], v[212:215], v[44:47]
	v_mfma_f32_16x16x32_bf16 v[40:43], v[164:167], v[212:215], v[40:43]
	v_mfma_f32_16x16x32_bf16 v[28:31], v[86:89], v[220:223], v[28:31]
	v_mfma_f32_16x16x32_bf16 v[24:27], v[164:167], v[220:223], v[24:27]
	v_mfma_f32_16x16x32_bf16 v[12:15], v[86:89], v[228:231], v[12:15]
	v_mfma_f32_16x16x32_bf16 v[8:11], v[164:167], v[228:231], v[8:11]
	v_mfma_f32_16x16x32_bf16 v[60:63], v[90:93], v[208:211], v[60:63]
	v_mfma_f32_16x16x32_bf16 v[56:59], v[168:171], v[208:211], v[56:59]
	v_mfma_f32_16x16x32_bf16 v[44:47], v[90:93], v[216:219], v[44:47]
	v_mfma_f32_16x16x32_bf16 v[40:43], v[168:171], v[216:219], v[40:43]
	v_mfma_f32_16x16x32_bf16 v[28:31], v[90:93], v[224:227], v[28:31]
	v_mfma_f32_16x16x32_bf16 v[24:27], v[168:171], v[224:227], v[24:27]
	v_mfma_f32_16x16x32_bf16 v[12:15], v[90:93], v[242:245], v[12:15]
	v_mfma_f32_16x16x32_bf16 v[8:11], v[168:171], v[242:245], v[8:11]
	s_setprio 0
	s_setprio 1
	v_mfma_f32_16x16x32_bf16 v[52:55], v[172:175], v[188:191], v[52:55]
	v_mfma_f32_16x16x32_bf16 v[48:51], v[180:183], v[188:191], v[48:51]
	v_mfma_f32_16x16x32_bf16 v[36:39], v[172:175], v[212:215], v[36:39]
	v_mfma_f32_16x16x32_bf16 v[32:35], v[180:183], v[212:215], v[32:35]
	v_mfma_f32_16x16x32_bf16 v[20:23], v[172:175], v[220:223], v[20:23]
	v_mfma_f32_16x16x32_bf16 v[16:19], v[180:183], v[220:223], v[16:19]
	v_mfma_f32_16x16x32_bf16 v[4:7], v[172:175], v[228:231], v[4:7]
	v_mfma_f32_16x16x32_bf16 v[0:3], v[180:183], v[228:231], v[0:3]
	v_mfma_f32_16x16x32_bf16 v[52:55], v[176:179], v[208:211], v[52:55]
	v_mfma_f32_16x16x32_bf16 v[48:51], v[184:187], v[208:211], v[48:51]
	v_mfma_f32_16x16x32_bf16 v[36:39], v[176:179], v[216:219], v[36:39]
	v_mfma_f32_16x16x32_bf16 v[32:35], v[184:187], v[216:219], v[32:35]
	v_mfma_f32_16x16x32_bf16 v[20:23], v[176:179], v[224:227], v[20:23]
	v_mfma_f32_16x16x32_bf16 v[16:19], v[184:187], v[224:227], v[16:19]
	v_mfma_f32_16x16x32_bf16 v[4:7], v[176:179], v[242:245], v[4:7]
	v_mfma_f32_16x16x32_bf16 v[0:3], v[184:187], v[242:245], v[0:3]
	s_setprio 0
	s_barrier
	s_add_i32 s76, s76, 2
	s_add_u32 s38, s38, 0x100
	s_addc_u32 s39, s39, 0
	s_add_u32 s74, s74, 0x100
	s_addc_u32 s75, s75, 0
	s_cmp_gt_u32 s76, 13
	s_branch .LBB0_374

; #define PG8_LAS __attribute__((address_space(3)))
; #define PG8_STAGE(bufoff, gbase, voff) do { _Pragma("unroll") for (int _i = 0; _i < 2; ++_i) \
;         __builtin_amdgcn_global_load_lds((const unsigned*)((const char*)(gbase) + (voff)[_i]), (PG8_LAS unsigned*)(lds + (bufoff) + ldsw + _i * (8 * USTR)), 16, 0, 0); } while (0)
; #define PG8_WAIT_V(n) asm volatile("s_waitcnt vmcnt(" #n ")" ::: "memory")
; #define PG8_WAIT_L(n) asm volatile("s_waitcnt lgkmcnt(" #n ")" ::: "memory")
; #define PG8_BAR __builtin_amdgcn_s_barrier()
; template <class Epi, class Sched, bool ALIGN_EPI, bool SP2>
; __device__ __forceinline__ void gemm_phase(PG8_LAS unsigned char* lds, const Gemm g, const Sched& S, const Epi& E, int wid) {
;     ...
;         const bool has_next = S.next(ui + 1, nxt);
;         const char* nA = has_next ? (const char*)g.A + (size_t)nxt.pm * tstepA : cA; const char* nB = has_next ? (const char*)g.Bt + (size_t)nxt.pn * tstepB : cB;
;         for (int t = 0; t < nt; t += 2) {
;             const bool last = (t == nt - 2);
;             const char* a1 = cA + (size_t)(t + 1) * kstep;
;             const char* a2 = last ? nA : cA + (size_t)(t + 2) * kstep; const char* b2 = last ? nB : cB + (size_t)(t + 2) * kstep;
;             const char* a3 = a2 + kstep; const char* b3 = b2 + kstep;
;             if constexpr (Epi::PRE == 1) { if (last) {
;                 const char* rsrc; const char* ssrc; E.pre(cur, rsrc, ssrc);
; #pragma unroll
;                 for (int _i = 0; _i < 2; ++_i) __builtin_amdgcn_global_load_lds((const unsigned*)(rsrc + (wid + 8 * _i) * 1024 + lane * 16), (PG8_LAS unsigned*)(lds + LDS_XOFF + (wid + 8 * _i) * 1024), 16, 0, 0);
;                 if (wid == 0) __builtin_amdgcn_global_load_lds((const unsigned*)(ssrc + lane * 16), (PG8_LAS unsigned*)(lds + LDS_XOFF + 16384), 16, 0, 0);
;             } }
;             if constexpr (SP2) {
;             PG8_LDB(B0, 0, 0); PG8_LDB(B1, 0, 1); PG8_SCHED; PG8_LDA(At, 0, 0); PG8_STAGE(PG8_SA(1, 1), a1 + hstepA, voffA);
;             PG8_WAIT_V(8); PG8_WAIT_L(0); PG8_BAR; PG8_MMA(0, 0, At, B0); PG8_MMA(0, 1, At, B1); PG8_BAR; PG8_SCHED;
;             PG8_LDA(At, 0, 1); PG8_STAGE(PG8_SB(0, 0), b2, voffB); PG8_STAGE(PG8_SB(0, 1), b2 + hstepB, voffB); PG8_STAGE(PG8_SA(0, 0), a2, voffA);
;             PG8_WAIT_V(8); PG8_WAIT_L(0); PG8_BAR; PG8_MMA(1, 0, At, B0); PG8_MMA(1, 1, At, B1); PG8_BAR; PG8_SCHED;
.LBB0_392:
	s_ashr_i32 s69, s68, 31
	s_lshl_b64 s[22:23], s[68:69], 19
	s_add_u32 s74, s8, s22
	s_addc_u32 s75, s9, s23
	s_and_b64 s[22:23], s[36:37], exec
	s_cselect_b32 s10, s75, s39
	s_cselect_b32 s44, s74, s38
	s_ashr_i32 s73, s72, 31
	s_lshl_b64 s[22:23], s[72:73], 19
	v_readlane_b32 s27, v255, 20
	s_add_u32 s78, s27, s22
	v_readlane_b32 s22, v255, 21
	s_addc_u32 s79, s22, s23
	s_and_b64 s[22:23], s[36:37], exec
	s_cselect_b32 s45, s79, s41
	s_cselect_b32 s69, s78, s40
	s_lshl_b32 s22, s26, 8
	s_add_i32 s27, s22, 0xffff8000
	s_ashr_i32 s23, s22, 31
	s_lshr_b32 s27, s27, 14
	s_lshl_b64 s[42:43], s[22:23], 6
	s_ashr_i32 s23, s26, 4
	s_add_i32 s27, s27, 8
	s_cmpk_lt_i32 s26, 0x80
	v_lshl_add_u64 v[0:1], v[152:153], 0, s[42:43]
	v_readlane_b32 s42, v252, 20
	s_cselect_b32 s23, s23, s27
	s_lshl_b32 s26, s2, 8
	v_readlane_b32 s43, v252, 21
	s_mul_hi_i32 s70, s23, 0x2800
	s_mulk_i32 s23, 0x2800
	s_ashr_i32 s27, s26, 31
	v_lshl_add_u64 v[18:19], v[0:1], 0, s[42:43]
	v_readlane_b32 s42, v254, 36
	s_add_u32 s23, s42, s23
	v_readlane_b32 s42, v254, 37
	s_addc_u32 s70, s42, s70
	s_lshl_b64 s[42:43], s[26:27], 2
	s_add_u32 s42, s23, s42
	s_addc_u32 s43, s70, s43
	s_add_u32 s38, s38, 0x40080
	s_addc_u32 s39, s39, 0
	v_lshl_add_u64 v[16:17], v[0:1], 0, s[18:19]
	s_add_u32 s23, s40, 0x100
	s_waitcnt lgkmcnt(0)
	v_lshl_add_u64 v[20:21], s[42:43], 0, v[144:145]
	s_addc_u32 s70, s41, 0
	s_mov_b32 s71, -2
	s_cmp_eq_u32 s71, 12
	s_cselect_b64 s[40:41], -1, 0
	s_add_u32 s42, s38, 0xfffc0080
	s_addc_u32 s43, s39, -1
	s_and_b64 s[40:41], s[40:41], exec
	s_cselect_b32 s43, s10, s43
	s_cselect_b32 s42, s44, s42
	s_cselect_b32 s41, s45, s70
	s_cselect_b32 s40, s69, s23
	s_add_i32 s73, 0, 0x11000
	v_add_u32_e32 v30, s73, v197
	s_add_i32 vcc_lo, 0, 0x15400
	ds_read_b128 v[22:25], v30
	ds_read_b128 v[26:29], v30 offset:64
	ds_read_b128 v[158:161], v30 offset:2176
	ds_read_b128 v[162:165], v30 offset:2240
	v_add_u32_e32 v30, vcc_lo, v197
	ds_read_b128 v[166:169], v30
	ds_read_b128 v[170:173], v30 offset:64
	ds_read_b128 v[174:177], v30 offset:2176
	ds_read_b128 v[178:181], v30 offset:2240
	v_lshl_add_u64 v[30:31], s[38:39], 0, v[154:155]
	s_add_i32 m0, s95, 0xcc00
	ds_read_b128 v[182:185], v210
	ds_read_b128 v[186:189], v210 offset:64
	ds_read_b128 v[212:215], v210 offset:2176
	ds_read_b128 v[216:219], v210 offset:2240
	ds_read_b128 v[220:223], v210 offset:4352
	ds_read_b128 v[224:227], v210 offset:4416
	ds_read_b128 v[228:231], v210 offset:6528
	ds_read_b128 v[242:245], v210 offset:6592
	global_load_lds_dwordx4 v[30:31], off
	v_lshl_add_u64 v[30:31], s[38:39], 0, v[156:157]
	s_add_i32 m0, s95, 0xee00
	s_nop 0
	global_load_lds_dwordx4 v[30:31], off
	s_waitcnt vmcnt(8)
	s_waitcnt lgkmcnt(0)
	s_barrier
	s_setprio 1
	s_waitcnt lgkmcnt(0)
	v_mfma_f32_16x16x32_bf16 v[140:143], v[22:25], v[182:185], 0
	v_mfma_f32_16x16x32_bf16 v[136:139], v[158:161], v[182:185], 0
	v_mfma_f32_16x16x32_bf16 v[124:127], v[22:25], v[212:215], 0
	v_mfma_f32_16x16x32_bf16 v[120:123], v[158:161], v[212:215], 0
	v_mfma_f32_16x16x32_bf16 v[108:111], v[22:25], v[220:223], 0
	v_mfma_f32_16x16x32_bf16 v[104:107], v[158:161], v[220:223], 0
	v_mfma_f32_16x16x32_bf16 v[92:95], v[22:25], v[228:231], 0
	v_mfma_f32_16x16x32_bf16 v[88:91], v[158:161], v[228:231], 0
	v_mfma_f32_16x16x32_bf16 v[140:143], v[26:29], v[186:189], v[140:143]
	v_mfma_f32_16x16x32_bf16 v[136:139], v[162:165], v[186:189], v[136:139]
	v_mfma_f32_16x16x32_bf16 v[124:127], v[26:29], v[216:219], v[124:127]
	v_mfma_f32_16x16x32_bf16 v[120:123], v[162:165], v[216:219], v[120:123]
	v_mfma_f32_16x16x32_bf16 v[108:111], v[26:29], v[224:227], v[108:111]
	v_mfma_f32_16x16x32_bf16 v[104:107], v[162:165], v[224:227], v[104:107]
	v_mfma_f32_16x16x32_bf16 v[92:95], v[26:29], v[242:245], v[92:95]
	v_mfma_f32_16x16x32_bf16 v[88:91], v[162:165], v[242:245], v[88:91]
	s_setprio 0
	s_setprio 1
	v_mfma_f32_16x16x32_bf16 v[132:135], v[166:169], v[182:185], 0
	v_mfma_f32_16x16x32_bf16 v[128:131], v[174:177], v[182:185], 0
	v_mfma_f32_16x16x32_bf16 v[116:119], v[166:169], v[212:215], 0
	v_mfma_f32_16x16x32_bf16 v[112:115], v[174:177], v[212:215], 0
	v_mfma_f32_16x16x32_bf16 v[100:103], v[166:169], v[220:223], 0
	v_mfma_f32_16x16x32_bf16 v[96:99], v[174:177], v[220:223], 0
	v_mfma_f32_16x16x32_bf16 v[84:87], v[166:169], v[228:231], 0
	v_mfma_f32_16x16x32_bf16 v[80:83], v[174:177], v[228:231], 0
	v_mfma_f32_16x16x32_bf16 v[132:135], v[170:173], v[186:189], v[132:135]
	v_mfma_f32_16x16x32_bf16 v[128:131], v[178:181], v[186:189], v[128:131]
	v_mfma_f32_16x16x32_bf16 v[116:119], v[170:173], v[216:219], v[116:119]
	v_mfma_f32_16x16x32_bf16 v[112:115], v[178:181], v[216:219], v[112:115]
	v_mfma_f32_16x16x32_bf16 v[100:103], v[170:173], v[224:227], v[100:103]
	v_mfma_f32_16x16x32_bf16 v[96:99], v[178:181], v[224:227], v[96:99]
	v_mfma_f32_16x16x32_bf16 v[84:87], v[170:173], v[242:245], v[84:87]
	v_mfma_f32_16x16x32_bf16 v[80:83], v[178:181], v[242:245], v[80:83]
	s_setprio 0
	s_barrier
	s_add_i32 s73, s73, s33
	v_lshl_add_u64 v[190:191], s[40:41], 0, v[192:193]
	s_mov_b32 m0, s73
	ds_read_b128 v[182:185], v210 offset:17408
	ds_read_b128 v[186:189], v210 offset:17472
	ds_read_b128 v[212:215], v210 offset:19584
	ds_read_b128 v[216:219], v210 offset:19648
	ds_read_b128 v[220:223], v210 offset:21760
	ds_read_b128 v[224:227], v210 offset:21824
	ds_read_b128 v[228:231], v210 offset:23936
	ds_read_b128 v[242:245], v210 offset:24000
	global_load_lds_dwordx4 v[190:191], off
	s_add_i32 m0, s73, 0x2200
	s_add_u32 s76, s40, 0x40000
	v_lshl_add_u64 v[198:199], s[40:41], 0, v[146:147]
	s_addc_u32 s77, s41, 0
	s_add_i32 s73, vcc_lo, s33
	global_load_lds_dwordx4 v[198:199], off
	v_lshl_add_u64 v[30:31], s[76:77], 0, v[192:193]
	s_mov_b32 m0, s73
	v_lshl_add_u64 v[200:201], s[42:43], 0, v[150:151]
	global_load_lds_dwordx4 v[30:31], off
	v_lshl_add_u64 v[30:31], s[76:77], 0, v[146:147]
	s_add_i32 m0, s73, 0x2200
	v_lshl_add_u64 v[208:209], s[42:43], 0, v[148:149]
	global_load_lds_dwordx4 v[30:31], off
	s_mov_b32 m0, s95
	s_nop 0
	global_load_lds_dwordx4 v[200:201], off
	s_mov_b32 m0, s5
	s_nop 0
	global_load_lds_dwordx4 v[208:209], off
	s_waitcnt vmcnt(8)
	s_waitcnt lgkmcnt(0)
	s_barrier
; #define PG8_STAGE(bufoff, gbase, voff) do { _Pragma("unroll") for (int _i = 0; _i < 2; ++_i) \
;         __builtin_amdgcn_global_load_lds((const unsigned*)((const char*)(gbase) + (voff)[_i]), (PG8_LAS unsigned*)(lds + (bufoff) + ldsw + _i * (8 * USTR)), 16, 0, 0); } while (0)
; #define PG8_LDA(dst, b, h) do { _Pragma("unroll") for (int m = 0; m < 4; ++m) _Pragma("unroll") for (int k = 0; k < 2; ++k) dst[m][k] = *(const PG8_LAS bf16x8*)(lds + PG8_SA(b, h) + aoff + m * (2 * USTR) + k * 64); } while (0)
; #define PG8_LDB(dst, b, h) do { _Pragma("unroll") for (int n = 0; n < 2; ++n) _Pragma("unroll") for (int k = 0; k < 2; ++k) dst[n][k] = *(const PG8_LAS bf16x8*)(lds + PG8_SB(b, h) + boff + n * (2 * USTR) + k * 64); } while (0)
; #define PG8_MMA(ai, bj, At, Bt) do { __builtin_amdgcn_s_setprio(1); _Pragma("unroll") for (int m = 0; m < 4; ++m) _Pragma("unroll") for (int n = 0; n < 2; ++n) _Pragma("unroll") for (int k = 0; k < 2; ++k) \
;         acc[ai][bj][m][n] = __builtin_amdgcn_mfma_f32_16x16x32_bf16(Bt[n][k], At[m][k], acc[ai][bj][m][n], 0, 0, 0); __builtin_amdgcn_s_setprio(0); } while (0)
; #define PG8_WAIT_V(n) asm volatile("s_waitcnt vmcnt(" #n ")" ::: "memory")
; #define PG8_WAIT_L(n) asm volatile("s_waitcnt lgkmcnt(" #n ")" ::: "memory")
; #define PG8_BAR __builtin_amdgcn_s_barrier()
; #define PG8_SCHED __builtin_amdgcn_sched_barrier(0)
; template <class Epi, class Sched, bool ALIGN_EPI, bool SP2>
; __device__ __forceinline__ void gemm_phase(PG8_LAS unsigned char* lds, const Gemm g, const Sched& S, const Epi& E, int wid) {
;     ...
;             PG8_WAIT_V(8); PG8_WAIT_L(0); PG8_BAR; PG8_MMA(1, 0, At, B0); PG8_MMA(1, 1, At, B1); PG8_BAR; PG8_SCHED;
;             PG8_LDB(B0, 1, 0); PG8_LDB(B1, 1, 1); PG8_SCHED; PG8_LDA(At, 1, 0); PG8_STAGE(PG8_SA(0, 1), a2 + hstepA, voffA);
;             PG8_WAIT_V(8); PG8_WAIT_L(0); PG8_BAR; PG8_MMA(0, 0, At, B0); PG8_MMA(0, 1, At, B1); PG8_BAR; PG8_SCHED;
	s_setprio 1
	s_waitcnt lgkmcnt(0)
	v_mfma_f32_16x16x32_bf16 v[76:79], v[22:25], v[182:185], 0
	v_mfma_f32_16x16x32_bf16 v[72:75], v[158:161], v[182:185], 0
	v_mfma_f32_16x16x32_bf16 v[60:63], v[22:25], v[212:215], 0
	v_mfma_f32_16x16x32_bf16 v[56:59], v[158:161], v[212:215], 0
	v_mfma_f32_16x16x32_bf16 v[44:47], v[22:25], v[220:223], 0
	v_mfma_f32_16x16x32_bf16 v[40:43], v[158:161], v[220:223], 0
	v_mfma_f32_16x16x32_bf16 v[12:15], v[22:25], v[228:231], 0
	v_mfma_f32_16x16x32_bf16 v[8:11], v[158:161], v[228:231], 0
	v_mfma_f32_16x16x32_bf16 v[76:79], v[26:29], v[186:189], v[76:79]
	v_mfma_f32_16x16x32_bf16 v[72:75], v[162:165], v[186:189], v[72:75]
	v_mfma_f32_16x16x32_bf16 v[60:63], v[26:29], v[216:219], v[60:63]
	v_mfma_f32_16x16x32_bf16 v[56:59], v[162:165], v[216:219], v[56:59]
	v_mfma_f32_16x16x32_bf16 v[44:47], v[26:29], v[224:227], v[44:47]
	v_mfma_f32_16x16x32_bf16 v[40:43], v[162:165], v[224:227], v[40:43]
	v_mfma_f32_16x16x32_bf16 v[12:15], v[26:29], v[242:245], v[12:15]
	v_mfma_f32_16x16x32_bf16 v[8:11], v[162:165], v[242:245], v[8:11]
	s_setprio 0
	s_setprio 1
	v_mfma_f32_16x16x32_bf16 v[52:55], v[166:169], v[212:215], 0
	v_mfma_f32_16x16x32_bf16 v[48:51], v[174:177], v[212:215], 0
	v_mfma_f32_16x16x32_bf16 v[36:39], v[166:169], v[220:223], 0
	v_mfma_f32_16x16x32_bf16 v[30:33], v[174:177], v[220:223], 0
	v_mfma_f32_16x16x32_bf16 v[4:7], v[166:169], v[228:231], 0
	v_mfma_f32_16x16x32_bf16 v[0:3], v[174:177], v[228:231], 0
	v_mfma_f32_16x16x32_bf16 v[22:25], v[166:169], v[182:185], 0
	v_mfma_f32_16x16x32_bf16 v[26:29], v[174:177], v[182:185], 0
	v_mfma_f32_16x16x32_bf16 v[52:55], v[170:173], v[216:219], v[52:55]
	v_mfma_f32_16x16x32_bf16 v[48:51], v[178:181], v[216:219], v[48:51]
	v_mfma_f32_16x16x32_bf16 v[36:39], v[170:173], v[224:227], v[36:39]
	v_mfma_f32_16x16x32_bf16 v[30:33], v[178:181], v[224:227], v[30:33]
	v_mfma_f32_16x16x32_bf16 v[4:7], v[170:173], v[242:245], v[4:7]
	v_mfma_f32_16x16x32_bf16 v[0:3], v[178:181], v[242:245], v[0:3]
	v_mfma_f32_16x16x32_bf16 v[22:25], v[170:173], v[186:189], v[22:25]
	v_mfma_f32_16x16x32_bf16 v[26:29], v[178:181], v[186:189], v[26:29]
	s_setprio 0
	s_barrier
	s_add_i32 s73, 0, 0x19800
	v_add_u32_e32 v34, s73, v197
	s_add_i32 s76, 0, 0x1dc00
	ds_read_b128 v[64:67], v34
	ds_read_b128 v[68:71], v34 offset:64
	ds_read_b128 v[158:161], v34 offset:2176
	ds_read_b128 v[162:165], v34 offset:2240
	v_add_u32_e32 v34, s76, v197
	ds_read_b128 v[166:169], v34
	ds_read_b128 v[170:173], v34 offset:64
	ds_read_b128 v[174:177], v34 offset:2176
	ds_read_b128 v[178:181], v34 offset:2240
	s_add_u32 s42, s42, 0x40000
	s_addc_u32 s43, s43, 0
	s_mov_b32 m0, s56
	v_lshl_add_u64 v[34:35], s[42:43], 0, v[150:151]
	ds_read_b128 v[182:185], v210 offset:34816
	ds_read_b128 v[186:189], v210 offset:34880
	ds_read_b128 v[212:215], v210 offset:36992
	ds_read_b128 v[216:219], v210 offset:37056
	ds_read_b128 v[220:223], v210 offset:39168
	ds_read_b128 v[224:227], v210 offset:39232
	ds_read_b128 v[228:231], v210 offset:41344
	ds_read_b128 v[242:245], v210 offset:41408
	global_load_lds_dwordx4 v[34:35], off
	v_lshl_add_u64 v[34:35], s[42:43], 0, v[148:149]
	s_mov_b32 m0, s57
	s_nop 0
	global_load_lds_dwordx4 v[34:35], off
	s_waitcnt vmcnt(8)
	s_waitcnt lgkmcnt(0)
	s_barrier
	s_setprio 1
	s_waitcnt lgkmcnt(0)
	v_mfma_f32_16x16x32_bf16 v[140:143], v[64:67], v[182:185], v[140:143]
	v_mfma_f32_16x16x32_bf16 v[136:139], v[158:161], v[182:185], v[136:139]
	v_mfma_f32_16x16x32_bf16 v[124:127], v[64:67], v[212:215], v[124:127]
	v_mfma_f32_16x16x32_bf16 v[120:123], v[158:161], v[212:215], v[120:123]
	v_mfma_f32_16x16x32_bf16 v[108:111], v[64:67], v[220:223], v[108:111]
	v_mfma_f32_16x16x32_bf16 v[104:107], v[158:161], v[220:223], v[104:107]
	v_mfma_f32_16x16x32_bf16 v[92:95], v[64:67], v[228:231], v[92:95]
	v_mfma_f32_16x16x32_bf16 v[88:91], v[158:161], v[228:231], v[88:91]
	v_mfma_f32_16x16x32_bf16 v[140:143], v[68:71], v[186:189], v[140:143]
	v_mfma_f32_16x16x32_bf16 v[136:139], v[162:165], v[186:189], v[136:139]
	v_mfma_f32_16x16x32_bf16 v[124:127], v[68:71], v[216:219], v[124:127]
	v_mfma_f32_16x16x32_bf16 v[120:123], v[162:165], v[216:219], v[120:123]
	v_mfma_f32_16x16x32_bf16 v[108:111], v[68:71], v[224:227], v[108:111]
	v_mfma_f32_16x16x32_bf16 v[104:107], v[162:165], v[224:227], v[104:107]
	v_mfma_f32_16x16x32_bf16 v[92:95], v[68:71], v[242:245], v[92:95]
	v_mfma_f32_16x16x32_bf16 v[88:91], v[162:165], v[242:245], v[88:91]
	s_setprio 0
	s_setprio 1
	v_mfma_f32_16x16x32_bf16 v[132:135], v[166:169], v[182:185], v[132:135]
	v_mfma_f32_16x16x32_bf16 v[128:131], v[174:177], v[182:185], v[128:131]
	v_mfma_f32_16x16x32_bf16 v[116:119], v[166:169], v[212:215], v[116:119]
	v_mfma_f32_16x16x32_bf16 v[112:115], v[174:177], v[212:215], v[112:115]
	v_mfma_f32_16x16x32_bf16 v[100:103], v[166:169], v[220:223], v[100:103]
	v_mfma_f32_16x16x32_bf16 v[96:99], v[174:177], v[220:223], v[96:99]
	v_mfma_f32_16x16x32_bf16 v[84:87], v[166:169], v[228:231], v[84:87]
	v_mfma_f32_16x16x32_bf16 v[80:83], v[174:177], v[228:231], v[80:83]
	v_mfma_f32_16x16x32_bf16 v[132:135], v[170:173], v[186:189], v[132:135]
	v_mfma_f32_16x16x32_bf16 v[128:131], v[178:181], v[186:189], v[128:131]
	v_mfma_f32_16x16x32_bf16 v[116:119], v[170:173], v[216:219], v[116:119]
	v_mfma_f32_16x16x32_bf16 v[112:115], v[178:181], v[216:219], v[112:115]
	v_mfma_f32_16x16x32_bf16 v[100:103], v[170:173], v[224:227], v[100:103]
	v_mfma_f32_16x16x32_bf16 v[96:99], v[178:181], v[224:227], v[96:99]
	v_mfma_f32_16x16x32_bf16 v[84:87], v[170:173], v[242:245], v[84:87]
	v_mfma_f32_16x16x32_bf16 v[80:83], v[178:181], v[242:245], v[80:83]
	s_setprio 0
	s_barrier
; #define PG8_STAGE(bufoff, gbase, voff) do { _Pragma("unroll") for (int _i = 0; _i < 2; ++_i) \
;         __builtin_amdgcn_global_load_lds((const unsigned*)((const char*)(gbase) + (voff)[_i]), (PG8_LAS unsigned*)(lds + (bufoff) + ldsw + _i * (8 * USTR)), 16, 0, 0); } while (0)
; #define PG8_LDA(dst, b, h) do { _Pragma("unroll") for (int m = 0; m < 4; ++m) _Pragma("unroll") for (int k = 0; k < 2; ++k) dst[m][k] = *(const PG8_LAS bf16x8*)(lds + PG8_SA(b, h) + aoff + m * (2 * USTR) + k * 64); } while (0)
; #define PG8_MMA(ai, bj, At, Bt) do { __builtin_amdgcn_s_setprio(1); _Pragma("unroll") for (int m = 0; m < 4; ++m) _Pragma("unroll") for (int n = 0; n < 2; ++n) _Pragma("unroll") for (int k = 0; k < 2; ++k) \
;         acc[ai][bj][m][n] = __builtin_amdgcn_mfma_f32_16x16x32_bf16(Bt[n][k], At[m][k], acc[ai][bj][m][n], 0, 0, 0); __builtin_amdgcn_s_setprio(0); } while (0)
; #define PG8_WAIT_V(n) asm volatile("s_waitcnt vmcnt(" #n ")" ::: "memory")
; #define PG8_WAIT_L(n) asm volatile("s_waitcnt lgkmcnt(" #n ")" ::: "memory")
; #define PG8_BAR __builtin_amdgcn_s_barrier()
; #define PG8_SCHED __builtin_amdgcn_sched_barrier(0)
; template <class Epi, class Sched, bool ALIGN_EPI, bool SP2>
; __device__ __forceinline__ void gemm_phase(PG8_LAS unsigned char* lds, const Gemm g, const Sched& S, const Epi& E, int wid) {
;     ...
;             PG8_LDA(At, 1, 1); PG8_STAGE(PG8_SB(1, 0), b3, voffB); PG8_STAGE(PG8_SB(1, 1), b3 + hstepB, voffB); PG8_STAGE(PG8_SA(1, 0), a3, voffA);
;             PG8_WAIT_V(8); PG8_WAIT_L(0); PG8_BAR; PG8_MMA(1, 0, At, B0); PG8_MMA(1, 1, At, B1); PG8_BAR; PG8_SCHED;
	s_add_i32 s42, s73, s33
	v_lshl_add_u64 v[34:35], v[190:191], 0, s[6:7]
	s_mov_b32 m0, s42
	ds_read_b128 v[182:185], v210 offset:52224
	ds_read_b128 v[186:189], v210 offset:52288
	ds_read_b128 v[212:215], v210 offset:54400
	ds_read_b128 v[216:219], v210 offset:54464
	ds_read_b128 v[220:223], v210 offset:56576
	ds_read_b128 v[224:227], v210 offset:56640
	ds_read_b128 v[228:231], v210 offset:58752
	ds_read_b128 v[242:245], v210 offset:58816
	global_load_lds_dwordx4 v[34:35], off
	s_add_i32 m0, s42, 0x2200
	s_add_u32 s40, s40, 0x40080
	v_lshl_add_u64 v[34:35], v[198:199], 0, s[6:7]
	s_addc_u32 s41, s41, 0
	s_add_i32 s42, s76, s33
	global_load_lds_dwordx4 v[34:35], off
	v_lshl_add_u64 v[34:35], s[40:41], 0, v[192:193]
	s_mov_b32 m0, s42
	s_nop 0
	global_load_lds_dwordx4 v[34:35], off
	v_lshl_add_u64 v[34:35], s[40:41], 0, v[146:147]
	s_add_i32 m0, s42, 0x2200
	s_nop 0
	global_load_lds_dwordx4 v[34:35], off
	v_lshl_add_u64 v[34:35], v[200:201], 0, s[6:7]
	s_mov_b32 m0, s29
	s_nop 0
	global_load_lds_dwordx4 v[34:35], off
	v_lshl_add_u64 v[34:35], v[208:209], 0, s[6:7]
	s_mov_b32 m0, s0
	s_nop 0
	global_load_lds_dwordx4 v[34:35], off
	s_waitcnt vmcnt(8)
	s_waitcnt lgkmcnt(0)
	s_barrier
	s_setprio 1
	s_waitcnt lgkmcnt(0)
	v_mfma_f32_16x16x32_bf16 v[76:79], v[64:67], v[182:185], v[76:79]
	v_mfma_f32_16x16x32_bf16 v[72:75], v[158:161], v[182:185], v[72:75]
	v_mfma_f32_16x16x32_bf16 v[60:63], v[64:67], v[212:215], v[60:63]
	v_mfma_f32_16x16x32_bf16 v[56:59], v[158:161], v[212:215], v[56:59]
	v_mfma_f32_16x16x32_bf16 v[44:47], v[64:67], v[220:223], v[44:47]
	v_mfma_f32_16x16x32_bf16 v[40:43], v[158:161], v[220:223], v[40:43]
	v_mfma_f32_16x16x32_bf16 v[12:15], v[64:67], v[228:231], v[12:15]
	v_mfma_f32_16x16x32_bf16 v[8:11], v[158:161], v[228:231], v[8:11]
	v_mfma_f32_16x16x32_bf16 v[76:79], v[68:71], v[186:189], v[76:79]
	v_mfma_f32_16x16x32_bf16 v[72:75], v[162:165], v[186:189], v[72:75]
	v_mfma_f32_16x16x32_bf16 v[60:63], v[68:71], v[216:219], v[60:63]
	v_mfma_f32_16x16x32_bf16 v[56:59], v[162:165], v[216:219], v[56:59]
	v_mfma_f32_16x16x32_bf16 v[44:47], v[68:71], v[224:227], v[44:47]
	v_mfma_f32_16x16x32_bf16 v[40:43], v[162:165], v[224:227], v[40:43]
	v_mfma_f32_16x16x32_bf16 v[12:15], v[68:71], v[242:245], v[12:15]
	v_mfma_f32_16x16x32_bf16 v[8:11], v[162:165], v[242:245], v[8:11]
	s_setprio 0
	s_setprio 1
	v_mfma_f32_16x16x32_bf16 v[22:25], v[166:169], v[182:185], v[22:25]
	v_mfma_f32_16x16x32_bf16 v[68:71], v[170:173], v[186:189], v[22:25]
	v_mfma_f32_16x16x32_bf16 v[22:25], v[174:177], v[182:185], v[26:29]
	v_mfma_f32_16x16x32_bf16 v[64:67], v[178:181], v[186:189], v[22:25]
	v_mfma_f32_16x16x32_bf16 v[22:25], v[166:169], v[212:215], v[52:55]
	v_mfma_f32_16x16x32_bf16 v[52:55], v[170:173], v[216:219], v[22:25]
	v_mfma_f32_16x16x32_bf16 v[22:25], v[174:177], v[212:215], v[48:51]
	v_mfma_f32_16x16x32_bf16 v[48:51], v[178:181], v[216:219], v[22:25]
	v_mfma_f32_16x16x32_bf16 v[22:25], v[166:169], v[220:223], v[36:39]
	v_mfma_f32_16x16x32_bf16 v[36:39], v[170:173], v[224:227], v[22:25]
	v_mfma_f32_16x16x32_bf16 v[22:25], v[174:177], v[220:223], v[30:33]
	v_mfma_f32_16x16x32_bf16 v[4:7], v[166:169], v[228:231], v[4:7]
	v_mfma_f32_16x16x32_bf16 v[0:3], v[174:177], v[228:231], v[0:3]
	v_mfma_f32_16x16x32_bf16 v[32:35], v[178:181], v[224:227], v[22:25]
	v_mfma_f32_16x16x32_bf16 v[4:7], v[170:173], v[242:245], v[4:7]
	v_mfma_f32_16x16x32_bf16 v[0:3], v[178:181], v[242:245], v[0:3]
	s_setprio 0
	s_barrier
	s_add_i32 s71, s71, 2
	s_add_u32 s38, s38, 0x100
	s_addc_u32 s39, s39, 0
	s_add_u32 s23, s23, 0x100
	s_addc_u32 s70, s70, 0
	s_cmp_gt_u32 s71, 13
	s_branch .LBB0_394
